# GEMM main loops: dropped the priority drop/raise between the two MFMA blocks of a super-phase and the repeated lgkmcnt wait after the barrier
# speedup vs baseline: 1.0027x; 1.0027x over previous
.LBB0_165:
	ds_read_b128 v[162:165], v158
	ds_read_b128 v[166:169], v158 offset:1024
	ds_read_b128 v[170:173], v158 offset:2048
	ds_read_b128 v[174:177], v158 offset:3072
	ds_read_b128 v[178:181], v159
	ds_read_b128 v[182:185], v159 offset:1024
	ds_read_b128 v[186:189], v159 offset:2048
	ds_read_b128 v[190:193], v159 offset:3072
	s_add_u32 s65, s94, 0xfffc0080
	s_addc_u32 s66, s95, -1
	s_cmp_eq_u32 s53, 12
	s_cselect_b32 vcc_hi, s3, s66
	s_cselect_b32 vcc_lo, s5, s65
	s_cselect_b32 s97, s8, s52
	s_cselect_b32 s96, s12, s13
	v_lshl_add_u64 v[148:149], s[94:95], 0, v[140:141]
	s_add_i32 m0, s7, 0xc000
	ds_read_b128 v[198:201], v160
	ds_read_b128 v[202:205], v160 offset:1024
	ds_read_b128 v[206:209], v160 offset:2048
	ds_read_b128 v[210:213], v160 offset:3072
	ds_read_b128 v[214:217], v160 offset:4096
	ds_read_b128 v[218:221], v160 offset:5120
	ds_read_b128 v[222:225], v160 offset:6144
	ds_read_b128 v[226:229], v160 offset:7168
	global_load_lds_dwordx4 v[148:149], off
	v_lshl_add_u64 v[148:149], s[94:95], 0, v[142:143]
	s_add_i32 m0, s7, 0xe000
	s_nop 0
	global_load_lds_dwordx4 v[148:149], off
	s_waitcnt vmcnt(8)
	s_waitcnt lgkmcnt(0)
	s_barrier
	s_setprio 1
	v_mfma_f32_16x16x32_bf16 v[124:127], v[162:165], v[198:201], v[124:127]
	v_mfma_f32_16x16x32_bf16 v[120:123], v[170:173], v[198:201], v[120:123]
	v_mfma_f32_16x16x32_bf16 v[108:111], v[162:165], v[206:209], v[108:111]
	v_mfma_f32_16x16x32_bf16 v[104:107], v[170:173], v[206:209], v[104:107]
	v_mfma_f32_16x16x32_bf16 v[92:95], v[162:165], v[214:217], v[92:95]
	v_mfma_f32_16x16x32_bf16 v[88:91], v[170:173], v[214:217], v[88:91]
	v_mfma_f32_16x16x32_bf16 v[76:79], v[162:165], v[222:225], v[76:79]
	v_mfma_f32_16x16x32_bf16 v[72:75], v[170:173], v[222:225], v[72:75]
	v_mfma_f32_16x16x32_bf16 v[124:127], v[166:169], v[202:205], v[124:127]
	v_mfma_f32_16x16x32_bf16 v[120:123], v[174:177], v[202:205], v[120:123]
	v_mfma_f32_16x16x32_bf16 v[108:111], v[166:169], v[210:213], v[108:111]
	v_mfma_f32_16x16x32_bf16 v[104:107], v[174:177], v[210:213], v[104:107]
	v_mfma_f32_16x16x32_bf16 v[92:95], v[166:169], v[218:221], v[92:95]
	v_mfma_f32_16x16x32_bf16 v[88:91], v[174:177], v[218:221], v[88:91]
	v_mfma_f32_16x16x32_bf16 v[76:79], v[166:169], v[226:229], v[76:79]
	v_mfma_f32_16x16x32_bf16 v[72:75], v[174:177], v[226:229], v[72:75]
	v_mfma_f32_16x16x32_bf16 v[116:119], v[178:181], v[198:201], v[116:119]
	v_mfma_f32_16x16x32_bf16 v[112:115], v[186:189], v[198:201], v[112:115]
	v_mfma_f32_16x16x32_bf16 v[100:103], v[178:181], v[206:209], v[100:103]
	v_mfma_f32_16x16x32_bf16 v[96:99], v[186:189], v[206:209], v[96:99]
	v_mfma_f32_16x16x32_bf16 v[84:87], v[178:181], v[214:217], v[84:87]
	v_mfma_f32_16x16x32_bf16 v[80:83], v[186:189], v[214:217], v[80:83]
	v_mfma_f32_16x16x32_bf16 v[68:71], v[178:181], v[222:225], v[68:71]
	v_mfma_f32_16x16x32_bf16 v[64:67], v[186:189], v[222:225], v[64:67]
	v_mfma_f32_16x16x32_bf16 v[116:119], v[182:185], v[202:205], v[116:119]
	v_mfma_f32_16x16x32_bf16 v[112:115], v[190:193], v[202:205], v[112:115]
	v_mfma_f32_16x16x32_bf16 v[100:103], v[182:185], v[210:213], v[100:103]
	v_mfma_f32_16x16x32_bf16 v[96:99], v[190:193], v[210:213], v[96:99]
	v_mfma_f32_16x16x32_bf16 v[84:87], v[182:185], v[218:221], v[84:87]
	v_mfma_f32_16x16x32_bf16 v[80:83], v[190:193], v[218:221], v[80:83]
	v_mfma_f32_16x16x32_bf16 v[68:71], v[182:185], v[226:229], v[68:71]
	v_mfma_f32_16x16x32_bf16 v[64:67], v[190:193], v[226:229], v[64:67]
	s_setprio 0
	s_barrier
	s_add_i32 s65, s58, s75
	v_lshl_add_u64 v[148:149], s[96:97], 0, v[130:131]
	s_mov_b32 m0, s65
	ds_read_b128 v[198:201], v160 offset:16384
	ds_read_b128 v[202:205], v160 offset:17408
	ds_read_b128 v[206:209], v160 offset:18432
	ds_read_b128 v[210:213], v160 offset:19456
	ds_read_b128 v[214:217], v160 offset:20480
	ds_read_b128 v[218:221], v160 offset:21504
	ds_read_b128 v[222:225], v160 offset:22528
	ds_read_b128 v[226:229], v160 offset:23552
	global_load_lds_dwordx4 v[148:149], off
	s_add_i32 m0, s65, 0x2000
	s_add_u32 s66, s96, 0x40000
	v_lshl_add_u64 v[194:195], s[96:97], 0, v[134:135]
	s_addc_u32 s67, s97, 0
	s_add_i32 s65, s59, s75
	global_load_lds_dwordx4 v[194:195], off
	v_lshl_add_u64 v[230:231], s[66:67], 0, v[130:131]
	s_mov_b32 m0, s65
	v_lshl_add_u64 v[232:233], vcc, 0, v[132:133]
	global_load_lds_dwordx4 v[230:231], off
	v_lshl_add_u64 v[230:231], s[66:67], 0, v[134:135]
	s_add_i32 m0, s65, 0x2000
	s_nop 0
	global_load_lds_dwordx4 v[230:231], off
	v_lshl_add_u64 v[230:231], vcc, 0, v[128:129]
	s_mov_b32 m0, s7
	s_nop 0
	global_load_lds_dwordx4 v[230:231], off
	s_mov_b32 m0, s77
	s_nop 0
	global_load_lds_dwordx4 v[232:233], off
	s_waitcnt vmcnt(8)
	s_waitcnt lgkmcnt(0)
	s_barrier
	s_setprio 1
	v_mfma_f32_16x16x32_bf16 v[60:63], v[162:165], v[198:201], v[60:63]
	v_mfma_f32_16x16x32_bf16 v[56:59], v[170:173], v[198:201], v[56:59]
	v_mfma_f32_16x16x32_bf16 v[44:47], v[162:165], v[206:209], v[44:47]
	v_mfma_f32_16x16x32_bf16 v[40:43], v[170:173], v[206:209], v[40:43]
	v_mfma_f32_16x16x32_bf16 v[28:31], v[162:165], v[214:217], v[28:31]
	v_mfma_f32_16x16x32_bf16 v[24:27], v[170:173], v[214:217], v[24:27]
	v_mfma_f32_16x16x32_bf16 v[12:15], v[162:165], v[222:225], v[12:15]
	v_mfma_f32_16x16x32_bf16 v[8:11], v[170:173], v[222:225], v[8:11]
	v_mfma_f32_16x16x32_bf16 v[60:63], v[166:169], v[202:205], v[60:63]
	v_mfma_f32_16x16x32_bf16 v[56:59], v[174:177], v[202:205], v[56:59]
	v_mfma_f32_16x16x32_bf16 v[44:47], v[166:169], v[210:213], v[44:47]
	v_mfma_f32_16x16x32_bf16 v[40:43], v[174:177], v[210:213], v[40:43]
	v_mfma_f32_16x16x32_bf16 v[28:31], v[166:169], v[218:221], v[28:31]
	v_mfma_f32_16x16x32_bf16 v[24:27], v[174:177], v[218:221], v[24:27]
	v_mfma_f32_16x16x32_bf16 v[12:15], v[166:169], v[226:229], v[12:15]
	v_mfma_f32_16x16x32_bf16 v[8:11], v[174:177], v[226:229], v[8:11]
	v_mfma_f32_16x16x32_bf16 v[52:55], v[178:181], v[198:201], v[52:55]
	v_mfma_f32_16x16x32_bf16 v[48:51], v[186:189], v[198:201], v[48:51]
	v_mfma_f32_16x16x32_bf16 v[36:39], v[178:181], v[206:209], v[36:39]
	v_mfma_f32_16x16x32_bf16 v[32:35], v[186:189], v[206:209], v[32:35]
	v_mfma_f32_16x16x32_bf16 v[20:23], v[178:181], v[214:217], v[20:23]
	v_mfma_f32_16x16x32_bf16 v[16:19], v[186:189], v[214:217], v[16:19]
	v_mfma_f32_16x16x32_bf16 v[4:7], v[178:181], v[222:225], v[4:7]
	v_mfma_f32_16x16x32_bf16 v[0:3], v[186:189], v[222:225], v[0:3]
	v_mfma_f32_16x16x32_bf16 v[52:55], v[182:185], v[202:205], v[52:55]
	v_mfma_f32_16x16x32_bf16 v[48:51], v[190:193], v[202:205], v[48:51]
	v_mfma_f32_16x16x32_bf16 v[36:39], v[182:185], v[210:213], v[36:39]
	v_mfma_f32_16x16x32_bf16 v[32:35], v[190:193], v[210:213], v[32:35]
	v_mfma_f32_16x16x32_bf16 v[20:23], v[182:185], v[218:221], v[20:23]
	v_mfma_f32_16x16x32_bf16 v[16:19], v[190:193], v[218:221], v[16:19]
	v_mfma_f32_16x16x32_bf16 v[4:7], v[182:185], v[226:229], v[4:7]
	v_mfma_f32_16x16x32_bf16 v[0:3], v[190:193], v[226:229], v[0:3]
	s_setprio 0
	s_barrier
	s_add_i32 s65, 0, 0x18000
	v_add_u32_e32 v136, s65, v150
	s_add_i32 s70, 0, 0x1c000
	ds_read_b128 v[162:165], v136
	ds_read_b128 v[166:169], v136 offset:1024
	ds_read_b128 v[170:173], v136 offset:2048
	ds_read_b128 v[174:177], v136 offset:3072
	v_add_u32_e32 v136, s70, v150
	ds_read_b128 v[178:181], v136
	ds_read_b128 v[182:185], v136 offset:1024
	ds_read_b128 v[186:189], v136 offset:2048
	ds_read_b128 v[190:193], v136 offset:3072
	s_add_u32 s66, vcc_lo, 0x40000
	s_addc_u32 s67, vcc_hi, 0
	s_mov_b32 m0, s78
	v_lshl_add_u64 v[234:235], s[66:67], 0, v[128:129]
	ds_read_b128 v[198:201], v160 offset:32768
	ds_read_b128 v[202:205], v160 offset:33792
	ds_read_b128 v[206:209], v160 offset:34816
	ds_read_b128 v[210:213], v160 offset:35840
	ds_read_b128 v[214:217], v160 offset:36864
	ds_read_b128 v[218:221], v160 offset:37888
	ds_read_b128 v[222:225], v160 offset:38912
	ds_read_b128 v[226:229], v160 offset:39936
	global_load_lds_dwordx4 v[234:235], off
	v_lshl_add_u64 v[234:235], s[66:67], 0, v[132:133]
	s_mov_b32 m0, s79
	s_nop 0
	global_load_lds_dwordx4 v[234:235], off
	s_waitcnt vmcnt(8)
	s_waitcnt lgkmcnt(0)
	s_barrier
	s_setprio 1
	v_mfma_f32_16x16x32_bf16 v[124:127], v[162:165], v[198:201], v[124:127]
	v_mfma_f32_16x16x32_bf16 v[120:123], v[170:173], v[198:201], v[120:123]
	v_mfma_f32_16x16x32_bf16 v[108:111], v[162:165], v[206:209], v[108:111]
	v_mfma_f32_16x16x32_bf16 v[104:107], v[170:173], v[206:209], v[104:107]
	v_mfma_f32_16x16x32_bf16 v[92:95], v[162:165], v[214:217], v[92:95]
	v_mfma_f32_16x16x32_bf16 v[88:91], v[170:173], v[214:217], v[88:91]
	v_mfma_f32_16x16x32_bf16 v[76:79], v[162:165], v[222:225], v[76:79]
	v_mfma_f32_16x16x32_bf16 v[72:75], v[170:173], v[222:225], v[72:75]
	v_mfma_f32_16x16x32_bf16 v[124:127], v[166:169], v[202:205], v[124:127]
	v_mfma_f32_16x16x32_bf16 v[120:123], v[174:177], v[202:205], v[120:123]
	v_mfma_f32_16x16x32_bf16 v[108:111], v[166:169], v[210:213], v[108:111]
	v_mfma_f32_16x16x32_bf16 v[104:107], v[174:177], v[210:213], v[104:107]
	v_mfma_f32_16x16x32_bf16 v[92:95], v[166:169], v[218:221], v[92:95]
	v_mfma_f32_16x16x32_bf16 v[88:91], v[174:177], v[218:221], v[88:91]
	v_mfma_f32_16x16x32_bf16 v[76:79], v[166:169], v[226:229], v[76:79]
	v_mfma_f32_16x16x32_bf16 v[72:75], v[174:177], v[226:229], v[72:75]
	v_mfma_f32_16x16x32_bf16 v[116:119], v[178:181], v[198:201], v[116:119]
	v_mfma_f32_16x16x32_bf16 v[112:115], v[186:189], v[198:201], v[112:115]
	v_mfma_f32_16x16x32_bf16 v[100:103], v[178:181], v[206:209], v[100:103]
	v_mfma_f32_16x16x32_bf16 v[96:99], v[186:189], v[206:209], v[96:99]
	v_mfma_f32_16x16x32_bf16 v[84:87], v[178:181], v[214:217], v[84:87]
	v_mfma_f32_16x16x32_bf16 v[80:83], v[186:189], v[214:217], v[80:83]
	v_mfma_f32_16x16x32_bf16 v[68:71], v[178:181], v[222:225], v[68:71]
	v_mfma_f32_16x16x32_bf16 v[64:67], v[186:189], v[222:225], v[64:67]
	v_mfma_f32_16x16x32_bf16 v[116:119], v[182:185], v[202:205], v[116:119]
	v_mfma_f32_16x16x32_bf16 v[112:115], v[190:193], v[202:205], v[112:115]
	v_mfma_f32_16x16x32_bf16 v[100:103], v[182:185], v[210:213], v[100:103]
	v_mfma_f32_16x16x32_bf16 v[96:99], v[190:193], v[210:213], v[96:99]
	v_mfma_f32_16x16x32_bf16 v[84:87], v[182:185], v[218:221], v[84:87]
	v_mfma_f32_16x16x32_bf16 v[80:83], v[190:193], v[218:221], v[80:83]
	v_mfma_f32_16x16x32_bf16 v[68:71], v[182:185], v[226:229], v[68:71]
	v_mfma_f32_16x16x32_bf16 v[64:67], v[190:193], v[226:229], v[64:67]
	s_setprio 0
	s_barrier
	s_add_i32 s65, s65, s75
	v_lshl_add_u64 v[148:149], v[148:149], 0, s[82:83]
	s_mov_b32 m0, s65
	ds_read_b128 v[198:201], v160 offset:49152
	ds_read_b128 v[202:205], v160 offset:50176
	ds_read_b128 v[206:209], v160 offset:51200
	ds_read_b128 v[210:213], v160 offset:52224
	ds_read_b128 v[214:217], v160 offset:53248
	ds_read_b128 v[218:221], v160 offset:54272
	ds_read_b128 v[222:225], v160 offset:55296
	ds_read_b128 v[226:229], v160 offset:56320
	global_load_lds_dwordx4 v[148:149], off
	s_add_i32 m0, s65, 0x2000
	s_add_u32 s66, s96, 0x40080
	v_lshl_add_u64 v[148:149], v[194:195], 0, s[82:83]
	s_addc_u32 s67, s97, 0
	s_add_i32 s65, s70, s75
	global_load_lds_dwordx4 v[148:149], off
	v_lshl_add_u64 v[148:149], s[66:67], 0, v[130:131]
	s_mov_b32 m0, s65
	s_nop 0
	global_load_lds_dwordx4 v[148:149], off
	v_lshl_add_u64 v[148:149], s[66:67], 0, v[134:135]
	s_add_i32 m0, s65, 0x2000
	s_nop 0
	global_load_lds_dwordx4 v[148:149], off
	v_lshl_add_u64 v[148:149], v[230:231], 0, s[82:83]
	s_mov_b32 m0, s55
	s_nop 0
	global_load_lds_dwordx4 v[148:149], off
	v_lshl_add_u64 v[148:149], v[232:233], 0, s[82:83]
	s_mov_b32 m0, s56
	s_nop 0
	global_load_lds_dwordx4 v[148:149], off
	s_waitcnt vmcnt(8)
	s_waitcnt lgkmcnt(0)
	s_barrier
	s_setprio 1
	v_mfma_f32_16x16x32_bf16 v[60:63], v[162:165], v[198:201], v[60:63]
	v_mfma_f32_16x16x32_bf16 v[56:59], v[170:173], v[198:201], v[56:59]
	v_mfma_f32_16x16x32_bf16 v[44:47], v[162:165], v[206:209], v[44:47]
	v_mfma_f32_16x16x32_bf16 v[40:43], v[170:173], v[206:209], v[40:43]
	v_mfma_f32_16x16x32_bf16 v[28:31], v[162:165], v[214:217], v[28:31]
	v_mfma_f32_16x16x32_bf16 v[24:27], v[170:173], v[214:217], v[24:27]
	v_mfma_f32_16x16x32_bf16 v[12:15], v[162:165], v[222:225], v[12:15]
	v_mfma_f32_16x16x32_bf16 v[8:11], v[170:173], v[222:225], v[8:11]
	v_mfma_f32_16x16x32_bf16 v[60:63], v[166:169], v[202:205], v[60:63]
	v_mfma_f32_16x16x32_bf16 v[56:59], v[174:177], v[202:205], v[56:59]
	v_mfma_f32_16x16x32_bf16 v[44:47], v[166:169], v[210:213], v[44:47]
	v_mfma_f32_16x16x32_bf16 v[40:43], v[174:177], v[210:213], v[40:43]
	v_mfma_f32_16x16x32_bf16 v[28:31], v[166:169], v[218:221], v[28:31]
	v_mfma_f32_16x16x32_bf16 v[24:27], v[174:177], v[218:221], v[24:27]
	v_mfma_f32_16x16x32_bf16 v[12:15], v[166:169], v[226:229], v[12:15]
	v_mfma_f32_16x16x32_bf16 v[8:11], v[174:177], v[226:229], v[8:11]
	v_mfma_f32_16x16x32_bf16 v[52:55], v[178:181], v[198:201], v[52:55]
	v_mfma_f32_16x16x32_bf16 v[48:51], v[186:189], v[198:201], v[48:51]
	v_mfma_f32_16x16x32_bf16 v[36:39], v[178:181], v[206:209], v[36:39]
	v_mfma_f32_16x16x32_bf16 v[32:35], v[186:189], v[206:209], v[32:35]
	v_mfma_f32_16x16x32_bf16 v[20:23], v[178:181], v[214:217], v[20:23]
	v_mfma_f32_16x16x32_bf16 v[16:19], v[186:189], v[214:217], v[16:19]
	v_mfma_f32_16x16x32_bf16 v[4:7], v[178:181], v[222:225], v[4:7]
	v_mfma_f32_16x16x32_bf16 v[0:3], v[186:189], v[222:225], v[0:3]
	v_mfma_f32_16x16x32_bf16 v[52:55], v[182:185], v[202:205], v[52:55]
	v_mfma_f32_16x16x32_bf16 v[48:51], v[190:193], v[202:205], v[48:51]
	v_mfma_f32_16x16x32_bf16 v[36:39], v[182:185], v[210:213], v[36:39]
	v_mfma_f32_16x16x32_bf16 v[32:35], v[190:193], v[210:213], v[32:35]
	v_mfma_f32_16x16x32_bf16 v[20:23], v[182:185], v[218:221], v[20:23]
	v_mfma_f32_16x16x32_bf16 v[16:19], v[190:193], v[218:221], v[16:19]
	v_mfma_f32_16x16x32_bf16 v[4:7], v[182:185], v[226:229], v[4:7]
	v_mfma_f32_16x16x32_bf16 v[0:3], v[190:193], v[226:229], v[0:3]
	s_setprio 0
	s_barrier
	s_add_i32 s53, s53, 2
	s_add_u32 s94, s94, 0x100
	s_addc_u32 s95, s95, 0
	s_add_u32 s13, s13, 0x100
	s_addc_u32 s52, s52, 0
	s_cmp_gt_u32 s53, 13
	s_cbranch_scc0 .LBB0_165
	s_and_b64 vcc, exec, s[84:85]
	s_cbranch_vccz .LBB0_168
	s_barrier

.LBB0_592:
	ds_read_b128 v[146:149], v151
	ds_read_b128 v[154:157], v151 offset:1024
	ds_read_b128 v[158:161], v151 offset:2048
	ds_read_b128 v[162:165], v151 offset:3072
	ds_read_b128 v[166:169], v152
	ds_read_b128 v[170:173], v152 offset:1024
	ds_read_b128 v[174:177], v152 offset:2048
	ds_read_b128 v[178:181], v152 offset:3072
	s_add_u32 s48, s90, 0xfffc0080
	s_addc_u32 s49, s91, -1
	s_cmp_eq_u32 s73, 12
	s_cselect_b32 s95, s8, s49
	s_cselect_b32 s94, s9, s48
	s_cselect_b32 s93, s67, s72
	s_cselect_b32 s92, s70, s71
	v_lshl_add_u64 v[194:195], s[90:91], 0, v[138:139]
	s_add_i32 m0, s46, 0xc000
	ds_read_b128 v[182:185], v153
	ds_read_b128 v[186:189], v153 offset:1024
	ds_read_b128 v[190:193], v153 offset:2048
	ds_read_b128 v[202:205], v153 offset:3072
	ds_read_b128 v[206:209], v153 offset:4096
	ds_read_b128 v[210:213], v153 offset:5120
	ds_read_b128 v[214:217], v153 offset:6144
	ds_read_b128 v[218:221], v153 offset:7168
	global_load_lds_dwordx4 v[194:195], off
	v_lshl_add_u64 v[194:195], s[90:91], 0, v[140:141]
	s_add_i32 m0, s46, 0xe000
	s_nop 0
	global_load_lds_dwordx4 v[194:195], off
	s_waitcnt vmcnt(8)
	s_waitcnt lgkmcnt(0)
	s_barrier
	s_setprio 1
	v_mfma_f32_16x16x32_bf16 v[124:127], v[146:149], v[182:185], v[124:127]
	v_mfma_f32_16x16x32_bf16 v[120:123], v[158:161], v[182:185], v[120:123]
	v_mfma_f32_16x16x32_bf16 v[108:111], v[146:149], v[190:193], v[108:111]
	v_mfma_f32_16x16x32_bf16 v[104:107], v[158:161], v[190:193], v[104:107]
	v_mfma_f32_16x16x32_bf16 v[92:95], v[146:149], v[206:209], v[92:95]
	v_mfma_f32_16x16x32_bf16 v[88:91], v[158:161], v[206:209], v[88:91]
	v_mfma_f32_16x16x32_bf16 v[76:79], v[146:149], v[214:217], v[76:79]
	v_mfma_f32_16x16x32_bf16 v[72:75], v[158:161], v[214:217], v[72:75]
	v_mfma_f32_16x16x32_bf16 v[124:127], v[154:157], v[186:189], v[124:127]
	v_mfma_f32_16x16x32_bf16 v[120:123], v[162:165], v[186:189], v[120:123]
	v_mfma_f32_16x16x32_bf16 v[108:111], v[154:157], v[202:205], v[108:111]
	v_mfma_f32_16x16x32_bf16 v[104:107], v[162:165], v[202:205], v[104:107]
	v_mfma_f32_16x16x32_bf16 v[92:95], v[154:157], v[210:213], v[92:95]
	v_mfma_f32_16x16x32_bf16 v[88:91], v[162:165], v[210:213], v[88:91]
	v_mfma_f32_16x16x32_bf16 v[76:79], v[154:157], v[218:221], v[76:79]
	v_mfma_f32_16x16x32_bf16 v[72:75], v[162:165], v[218:221], v[72:75]
	v_mfma_f32_16x16x32_bf16 v[116:119], v[166:169], v[182:185], v[116:119]
	v_mfma_f32_16x16x32_bf16 v[112:115], v[174:177], v[182:185], v[112:115]
	v_mfma_f32_16x16x32_bf16 v[100:103], v[166:169], v[190:193], v[100:103]
	v_mfma_f32_16x16x32_bf16 v[96:99], v[174:177], v[190:193], v[96:99]
	v_mfma_f32_16x16x32_bf16 v[84:87], v[166:169], v[206:209], v[84:87]
	v_mfma_f32_16x16x32_bf16 v[80:83], v[174:177], v[206:209], v[80:83]
	v_mfma_f32_16x16x32_bf16 v[68:71], v[166:169], v[214:217], v[68:71]
	v_mfma_f32_16x16x32_bf16 v[64:67], v[174:177], v[214:217], v[64:67]
	v_mfma_f32_16x16x32_bf16 v[116:119], v[170:173], v[186:189], v[116:119]
	v_mfma_f32_16x16x32_bf16 v[112:115], v[178:181], v[186:189], v[112:115]
	v_mfma_f32_16x16x32_bf16 v[100:103], v[170:173], v[202:205], v[100:103]
	v_mfma_f32_16x16x32_bf16 v[96:99], v[178:181], v[202:205], v[96:99]
	v_mfma_f32_16x16x32_bf16 v[84:87], v[170:173], v[210:213], v[84:87]
	v_mfma_f32_16x16x32_bf16 v[80:83], v[178:181], v[210:213], v[80:83]
	v_mfma_f32_16x16x32_bf16 v[68:71], v[170:173], v[218:221], v[68:71]
	v_mfma_f32_16x16x32_bf16 v[64:67], v[178:181], v[218:221], v[64:67]
	s_setprio 0
	s_barrier
	s_add_i32 s48, s61, s15
	v_lshl_add_u64 v[194:195], s[92:93], 0, v[132:133]
	s_mov_b32 m0, s48
	ds_read_b128 v[182:185], v153 offset:16384
	ds_read_b128 v[186:189], v153 offset:17408
	ds_read_b128 v[190:193], v153 offset:18432
	ds_read_b128 v[202:205], v153 offset:19456
	ds_read_b128 v[206:209], v153 offset:20480
	ds_read_b128 v[210:213], v153 offset:21504
	ds_read_b128 v[214:217], v153 offset:22528
	ds_read_b128 v[218:221], v153 offset:23552
	global_load_lds_dwordx4 v[194:195], off
	s_add_i32 m0, s48, 0x2000
	s_add_u32 s78, s92, 0x40000
	v_lshl_add_u64 v[222:223], s[92:93], 0, v[128:129]
	s_addc_u32 s79, s93, 0
	s_add_i32 s48, s64, s15
	global_load_lds_dwordx4 v[222:223], off
	v_lshl_add_u64 v[224:225], s[78:79], 0, v[132:133]
	s_mov_b32 m0, s48
	v_lshl_add_u64 v[226:227], s[94:95], 0, v[130:131]
	global_load_lds_dwordx4 v[224:225], off
	v_lshl_add_u64 v[224:225], s[78:79], 0, v[128:129]
	s_add_i32 m0, s48, 0x2000
	s_nop 0
	global_load_lds_dwordx4 v[224:225], off
	v_lshl_add_u64 v[224:225], s[94:95], 0, v[134:135]
	s_mov_b32 m0, s46
	s_nop 0
	global_load_lds_dwordx4 v[224:225], off
	s_mov_b32 m0, s47
	s_nop 0
	global_load_lds_dwordx4 v[226:227], off
	s_waitcnt vmcnt(8)
	s_waitcnt lgkmcnt(0)
	s_barrier
	s_setprio 1
	v_mfma_f32_16x16x32_bf16 v[60:63], v[146:149], v[182:185], v[60:63]
	v_mfma_f32_16x16x32_bf16 v[56:59], v[158:161], v[182:185], v[56:59]
	v_mfma_f32_16x16x32_bf16 v[44:47], v[146:149], v[190:193], v[44:47]
	v_mfma_f32_16x16x32_bf16 v[40:43], v[158:161], v[190:193], v[40:43]
	v_mfma_f32_16x16x32_bf16 v[28:31], v[146:149], v[206:209], v[28:31]
	v_mfma_f32_16x16x32_bf16 v[24:27], v[158:161], v[206:209], v[24:27]
	v_mfma_f32_16x16x32_bf16 v[12:15], v[146:149], v[214:217], v[12:15]
	v_mfma_f32_16x16x32_bf16 v[8:11], v[158:161], v[214:217], v[8:11]
	v_mfma_f32_16x16x32_bf16 v[60:63], v[154:157], v[186:189], v[60:63]
	v_mfma_f32_16x16x32_bf16 v[56:59], v[162:165], v[186:189], v[56:59]
	v_mfma_f32_16x16x32_bf16 v[44:47], v[154:157], v[202:205], v[44:47]
	v_mfma_f32_16x16x32_bf16 v[40:43], v[162:165], v[202:205], v[40:43]
	v_mfma_f32_16x16x32_bf16 v[28:31], v[154:157], v[210:213], v[28:31]
	v_mfma_f32_16x16x32_bf16 v[24:27], v[162:165], v[210:213], v[24:27]
	v_mfma_f32_16x16x32_bf16 v[12:15], v[154:157], v[218:221], v[12:15]
	v_mfma_f32_16x16x32_bf16 v[8:11], v[162:165], v[218:221], v[8:11]
	v_mfma_f32_16x16x32_bf16 v[52:55], v[166:169], v[182:185], v[52:55]
	v_mfma_f32_16x16x32_bf16 v[48:51], v[174:177], v[182:185], v[48:51]
	v_mfma_f32_16x16x32_bf16 v[36:39], v[166:169], v[190:193], v[36:39]
	v_mfma_f32_16x16x32_bf16 v[32:35], v[174:177], v[190:193], v[32:35]
	v_mfma_f32_16x16x32_bf16 v[20:23], v[166:169], v[206:209], v[20:23]
	v_mfma_f32_16x16x32_bf16 v[16:19], v[174:177], v[206:209], v[16:19]
	v_mfma_f32_16x16x32_bf16 v[4:7], v[166:169], v[214:217], v[4:7]
	v_mfma_f32_16x16x32_bf16 v[0:3], v[174:177], v[214:217], v[0:3]
	v_mfma_f32_16x16x32_bf16 v[52:55], v[170:173], v[186:189], v[52:55]
	v_mfma_f32_16x16x32_bf16 v[48:51], v[178:181], v[186:189], v[48:51]
	v_mfma_f32_16x16x32_bf16 v[36:39], v[170:173], v[202:205], v[36:39]
	v_mfma_f32_16x16x32_bf16 v[32:35], v[178:181], v[202:205], v[32:35]
	v_mfma_f32_16x16x32_bf16 v[20:23], v[170:173], v[210:213], v[20:23]
	v_mfma_f32_16x16x32_bf16 v[16:19], v[178:181], v[210:213], v[16:19]
	v_mfma_f32_16x16x32_bf16 v[4:7], v[170:173], v[218:221], v[4:7]
	v_mfma_f32_16x16x32_bf16 v[0:3], v[178:181], v[218:221], v[0:3]
	s_setprio 0
	s_barrier
	s_add_i32 s48, 0, 0x18000
	s_add_i32 s49, 0, 0x1c000
	v_add_u32_e32 v162, s48, v150
	v_add_u32_e32 v178, s49, v150
	ds_read_b128 v[146:149], v162
	ds_read_b128 v[154:157], v162 offset:1024
	ds_read_b128 v[158:161], v162 offset:2048
	ds_read_b128 v[162:165], v162 offset:3072
	ds_read_b128 v[166:169], v178
	ds_read_b128 v[170:173], v178 offset:1024
	ds_read_b128 v[174:177], v178 offset:2048
	ds_read_b128 v[178:181], v178 offset:3072
	s_add_u32 s78, s94, 0x40000
	s_addc_u32 s79, s95, 0
	s_mov_b32 m0, s52
	v_lshl_add_u64 v[228:229], s[78:79], 0, v[134:135]
	ds_read_b128 v[182:185], v153 offset:32768
	ds_read_b128 v[186:189], v153 offset:33792
	ds_read_b128 v[190:193], v153 offset:34816
	ds_read_b128 v[202:205], v153 offset:35840
	ds_read_b128 v[206:209], v153 offset:36864
	ds_read_b128 v[210:213], v153 offset:37888
	ds_read_b128 v[214:217], v153 offset:38912
	ds_read_b128 v[218:221], v153 offset:39936
	global_load_lds_dwordx4 v[228:229], off
	v_lshl_add_u64 v[228:229], s[78:79], 0, v[130:131]
	s_mov_b32 m0, s53
	s_nop 0
	global_load_lds_dwordx4 v[228:229], off
	s_waitcnt vmcnt(8)
	s_waitcnt lgkmcnt(0)
	s_barrier
	s_setprio 1
	v_mfma_f32_16x16x32_bf16 v[124:127], v[146:149], v[182:185], v[124:127]
	v_mfma_f32_16x16x32_bf16 v[120:123], v[158:161], v[182:185], v[120:123]
	v_mfma_f32_16x16x32_bf16 v[108:111], v[146:149], v[190:193], v[108:111]
	v_mfma_f32_16x16x32_bf16 v[104:107], v[158:161], v[190:193], v[104:107]
	v_mfma_f32_16x16x32_bf16 v[92:95], v[146:149], v[206:209], v[92:95]
	v_mfma_f32_16x16x32_bf16 v[88:91], v[158:161], v[206:209], v[88:91]
	v_mfma_f32_16x16x32_bf16 v[76:79], v[146:149], v[214:217], v[76:79]
	v_mfma_f32_16x16x32_bf16 v[72:75], v[158:161], v[214:217], v[72:75]
	v_mfma_f32_16x16x32_bf16 v[124:127], v[154:157], v[186:189], v[124:127]
	v_mfma_f32_16x16x32_bf16 v[120:123], v[162:165], v[186:189], v[120:123]
	v_mfma_f32_16x16x32_bf16 v[108:111], v[154:157], v[202:205], v[108:111]
	v_mfma_f32_16x16x32_bf16 v[104:107], v[162:165], v[202:205], v[104:107]
	v_mfma_f32_16x16x32_bf16 v[92:95], v[154:157], v[210:213], v[92:95]
	v_mfma_f32_16x16x32_bf16 v[88:91], v[162:165], v[210:213], v[88:91]
	v_mfma_f32_16x16x32_bf16 v[76:79], v[154:157], v[218:221], v[76:79]
	v_mfma_f32_16x16x32_bf16 v[72:75], v[162:165], v[218:221], v[72:75]
	v_mfma_f32_16x16x32_bf16 v[116:119], v[166:169], v[182:185], v[116:119]
	v_mfma_f32_16x16x32_bf16 v[112:115], v[174:177], v[182:185], v[112:115]
	v_mfma_f32_16x16x32_bf16 v[100:103], v[166:169], v[190:193], v[100:103]
	v_mfma_f32_16x16x32_bf16 v[96:99], v[174:177], v[190:193], v[96:99]
	v_mfma_f32_16x16x32_bf16 v[84:87], v[166:169], v[206:209], v[84:87]
	v_mfma_f32_16x16x32_bf16 v[80:83], v[174:177], v[206:209], v[80:83]
	v_mfma_f32_16x16x32_bf16 v[68:71], v[166:169], v[214:217], v[68:71]
	v_mfma_f32_16x16x32_bf16 v[64:67], v[174:177], v[214:217], v[64:67]
	v_mfma_f32_16x16x32_bf16 v[116:119], v[170:173], v[186:189], v[116:119]
	v_mfma_f32_16x16x32_bf16 v[112:115], v[178:181], v[186:189], v[112:115]
	v_mfma_f32_16x16x32_bf16 v[100:103], v[170:173], v[202:205], v[100:103]
	v_mfma_f32_16x16x32_bf16 v[96:99], v[178:181], v[202:205], v[96:99]
	v_mfma_f32_16x16x32_bf16 v[84:87], v[170:173], v[210:213], v[84:87]
	v_mfma_f32_16x16x32_bf16 v[80:83], v[178:181], v[210:213], v[80:83]
	v_mfma_f32_16x16x32_bf16 v[68:71], v[170:173], v[218:221], v[68:71]
	v_mfma_f32_16x16x32_bf16 v[64:67], v[178:181], v[218:221], v[64:67]
	s_setprio 0
	s_barrier
	s_add_i32 s48, s48, s15
	v_lshl_add_u64 v[194:195], v[194:195], 0, s[10:11]
	s_mov_b32 m0, s48
	ds_read_b128 v[182:185], v153 offset:49152
	ds_read_b128 v[186:189], v153 offset:50176
	ds_read_b128 v[190:193], v153 offset:51200
	ds_read_b128 v[202:205], v153 offset:52224
	ds_read_b128 v[206:209], v153 offset:53248
	ds_read_b128 v[210:213], v153 offset:54272
	ds_read_b128 v[214:217], v153 offset:55296
	ds_read_b128 v[218:221], v153 offset:56320
	global_load_lds_dwordx4 v[194:195], off
	s_add_i32 m0, s48, 0x2000
	s_add_u32 s78, s92, 0x40080
	v_lshl_add_u64 v[194:195], v[222:223], 0, s[10:11]
	s_addc_u32 s79, s93, 0
	s_add_i32 s48, s49, s15
	global_load_lds_dwordx4 v[194:195], off
	v_lshl_add_u64 v[194:195], s[78:79], 0, v[132:133]
	s_mov_b32 m0, s48
	s_nop 0
	global_load_lds_dwordx4 v[194:195], off
	v_lshl_add_u64 v[194:195], s[78:79], 0, v[128:129]
	s_add_i32 m0, s48, 0x2000
	s_nop 0
	global_load_lds_dwordx4 v[194:195], off
	v_lshl_add_u64 v[194:195], v[224:225], 0, s[10:11]
	s_mov_b32 m0, s54
	s_nop 0
	global_load_lds_dwordx4 v[194:195], off
	v_lshl_add_u64 v[194:195], v[226:227], 0, s[10:11]
	s_mov_b32 m0, s55
	s_nop 0
	global_load_lds_dwordx4 v[194:195], off
	s_waitcnt vmcnt(8)
	s_waitcnt lgkmcnt(0)
	s_barrier
	s_setprio 1
	v_mfma_f32_16x16x32_bf16 v[60:63], v[146:149], v[182:185], v[60:63]
	v_mfma_f32_16x16x32_bf16 v[56:59], v[158:161], v[182:185], v[56:59]
	v_mfma_f32_16x16x32_bf16 v[44:47], v[146:149], v[190:193], v[44:47]
	v_mfma_f32_16x16x32_bf16 v[40:43], v[158:161], v[190:193], v[40:43]
	v_mfma_f32_16x16x32_bf16 v[28:31], v[146:149], v[206:209], v[28:31]
	v_mfma_f32_16x16x32_bf16 v[24:27], v[158:161], v[206:209], v[24:27]
	v_mfma_f32_16x16x32_bf16 v[12:15], v[146:149], v[214:217], v[12:15]
	v_mfma_f32_16x16x32_bf16 v[8:11], v[158:161], v[214:217], v[8:11]
	v_mfma_f32_16x16x32_bf16 v[60:63], v[154:157], v[186:189], v[60:63]
	v_mfma_f32_16x16x32_bf16 v[56:59], v[162:165], v[186:189], v[56:59]
	v_mfma_f32_16x16x32_bf16 v[44:47], v[154:157], v[202:205], v[44:47]
	v_mfma_f32_16x16x32_bf16 v[40:43], v[162:165], v[202:205], v[40:43]
	v_mfma_f32_16x16x32_bf16 v[28:31], v[154:157], v[210:213], v[28:31]
	v_mfma_f32_16x16x32_bf16 v[24:27], v[162:165], v[210:213], v[24:27]
	v_mfma_f32_16x16x32_bf16 v[12:15], v[154:157], v[218:221], v[12:15]
	v_mfma_f32_16x16x32_bf16 v[8:11], v[162:165], v[218:221], v[8:11]
	v_mfma_f32_16x16x32_bf16 v[52:55], v[166:169], v[182:185], v[52:55]
	v_mfma_f32_16x16x32_bf16 v[48:51], v[174:177], v[182:185], v[48:51]
	v_mfma_f32_16x16x32_bf16 v[36:39], v[166:169], v[190:193], v[36:39]
	v_mfma_f32_16x16x32_bf16 v[32:35], v[174:177], v[190:193], v[32:35]
	v_mfma_f32_16x16x32_bf16 v[20:23], v[166:169], v[206:209], v[20:23]
	v_mfma_f32_16x16x32_bf16 v[16:19], v[174:177], v[206:209], v[16:19]
	v_mfma_f32_16x16x32_bf16 v[4:7], v[166:169], v[214:217], v[4:7]
	v_mfma_f32_16x16x32_bf16 v[0:3], v[174:177], v[214:217], v[0:3]
	v_mfma_f32_16x16x32_bf16 v[52:55], v[170:173], v[186:189], v[52:55]
	v_mfma_f32_16x16x32_bf16 v[48:51], v[178:181], v[186:189], v[48:51]
	v_mfma_f32_16x16x32_bf16 v[36:39], v[170:173], v[202:205], v[36:39]
	v_mfma_f32_16x16x32_bf16 v[32:35], v[178:181], v[202:205], v[32:35]
	v_mfma_f32_16x16x32_bf16 v[20:23], v[170:173], v[210:213], v[20:23]
	v_mfma_f32_16x16x32_bf16 v[16:19], v[178:181], v[210:213], v[16:19]
	v_mfma_f32_16x16x32_bf16 v[4:7], v[170:173], v[218:221], v[4:7]
	v_mfma_f32_16x16x32_bf16 v[0:3], v[178:181], v[218:221], v[0:3]
	s_setprio 0
	s_barrier
	s_add_i32 s73, s73, 2
	s_add_u32 s90, s90, 0x100
	s_addc_u32 s91, s91, 0
	s_add_u32 s71, s71, 0x100
	s_addc_u32 s72, s72, 0
	s_cmp_gt_u32 s73, 13
	s_cbranch_scc0 .LBB0_592
	s_and_b64 vcc, exec, s[62:63]
	s_cbranch_vccz .LBB0_595
	s_barrier

.LBB0_613:
	ds_read_b128 v[152:155], v148
	ds_read_b128 v[156:159], v148 offset:1024
	ds_read_b128 v[160:163], v148 offset:2048
	ds_read_b128 v[164:167], v148 offset:3072
	ds_read_b128 v[168:171], v149
	ds_read_b128 v[172:175], v149 offset:1024
	ds_read_b128 v[176:179], v149 offset:2048
	ds_read_b128 v[180:183], v149 offset:3072
	s_add_i32 s81, s80, 2
	s_add_u32 s48, s88, 0x80
	s_addc_u32 s49, s89, 0
	s_cmp_eq_u32 s61, s80
	s_cselect_b32 s91, s5, s49
	s_cselect_b32 s90, s4, s48
	s_cselect_b32 s93, s87, s79
	s_cselect_b32 s92, s86, s78
	s_mov_b32 m0, s70
	v_lshl_add_u64 v[222:223], s[88:89], 0, v[138:139]
	ds_read_b128 v[184:187], v150
	ds_read_b128 v[188:191], v150 offset:1024
	ds_read_b128 v[192:195], v150 offset:2048
	ds_read_b128 v[202:205], v150 offset:3072
	ds_read_b128 v[206:209], v150 offset:4096
	ds_read_b128 v[210:213], v150 offset:5120
	ds_read_b128 v[214:217], v150 offset:6144
	ds_read_b128 v[218:221], v150 offset:7168
	global_load_lds_dwordx4 v[222:223], off
	v_lshl_add_u64 v[222:223], s[88:89], 0, v[140:141]
	s_mov_b32 m0, s71
	s_nop 0
	global_load_lds_dwordx4 v[222:223], off
	s_waitcnt vmcnt(8)
	s_waitcnt lgkmcnt(0)
	s_barrier
	s_setprio 1
	v_mfma_f32_16x16x32_bf16 v[124:127], v[152:155], v[184:187], v[124:127]
	v_mfma_f32_16x16x32_bf16 v[120:123], v[160:163], v[184:187], v[120:123]
	v_mfma_f32_16x16x32_bf16 v[108:111], v[152:155], v[192:195], v[108:111]
	v_mfma_f32_16x16x32_bf16 v[104:107], v[160:163], v[192:195], v[104:107]
	v_mfma_f32_16x16x32_bf16 v[92:95], v[152:155], v[206:209], v[92:95]
	v_mfma_f32_16x16x32_bf16 v[88:91], v[160:163], v[206:209], v[88:91]
	v_mfma_f32_16x16x32_bf16 v[76:79], v[152:155], v[214:217], v[76:79]
	v_mfma_f32_16x16x32_bf16 v[72:75], v[160:163], v[214:217], v[72:75]
	v_mfma_f32_16x16x32_bf16 v[124:127], v[156:159], v[188:191], v[124:127]
	v_mfma_f32_16x16x32_bf16 v[120:123], v[164:167], v[188:191], v[120:123]
	v_mfma_f32_16x16x32_bf16 v[108:111], v[156:159], v[202:205], v[108:111]
	v_mfma_f32_16x16x32_bf16 v[104:107], v[164:167], v[202:205], v[104:107]
	v_mfma_f32_16x16x32_bf16 v[92:95], v[156:159], v[210:213], v[92:95]
	v_mfma_f32_16x16x32_bf16 v[88:91], v[164:167], v[210:213], v[88:91]
	v_mfma_f32_16x16x32_bf16 v[76:79], v[156:159], v[218:221], v[76:79]
	v_mfma_f32_16x16x32_bf16 v[72:75], v[164:167], v[218:221], v[72:75]
	v_mfma_f32_16x16x32_bf16 v[116:119], v[168:171], v[184:187], v[116:119]
	v_mfma_f32_16x16x32_bf16 v[112:115], v[176:179], v[184:187], v[112:115]
	v_mfma_f32_16x16x32_bf16 v[100:103], v[168:171], v[192:195], v[100:103]
	v_mfma_f32_16x16x32_bf16 v[96:99], v[176:179], v[192:195], v[96:99]
	v_mfma_f32_16x16x32_bf16 v[84:87], v[168:171], v[206:209], v[84:87]
	v_mfma_f32_16x16x32_bf16 v[80:83], v[176:179], v[206:209], v[80:83]
	v_mfma_f32_16x16x32_bf16 v[68:71], v[168:171], v[214:217], v[68:71]
	v_mfma_f32_16x16x32_bf16 v[64:67], v[176:179], v[214:217], v[64:67]
	v_mfma_f32_16x16x32_bf16 v[116:119], v[172:175], v[188:191], v[116:119]
	v_mfma_f32_16x16x32_bf16 v[112:115], v[180:183], v[188:191], v[112:115]
	v_mfma_f32_16x16x32_bf16 v[100:103], v[172:175], v[202:205], v[100:103]
	v_mfma_f32_16x16x32_bf16 v[96:99], v[180:183], v[202:205], v[96:99]
	v_mfma_f32_16x16x32_bf16 v[84:87], v[172:175], v[210:213], v[84:87]
	v_mfma_f32_16x16x32_bf16 v[80:83], v[180:183], v[210:213], v[80:83]
	v_mfma_f32_16x16x32_bf16 v[68:71], v[172:175], v[218:221], v[68:71]
	v_mfma_f32_16x16x32_bf16 v[64:67], v[180:183], v[218:221], v[64:67]
	s_setprio 0
	s_barrier
	s_mov_b32 m0, s72
	v_lshl_add_u64 v[222:223], s[92:93], 0, v[132:133]
	ds_read_b128 v[184:187], v150 offset:16384
	ds_read_b128 v[188:191], v150 offset:17408
	ds_read_b128 v[192:195], v150 offset:18432
	ds_read_b128 v[202:205], v150 offset:19456
	ds_read_b128 v[206:209], v150 offset:20480
	ds_read_b128 v[210:213], v150 offset:21504
	ds_read_b128 v[214:217], v150 offset:22528
	ds_read_b128 v[218:221], v150 offset:23552
	global_load_lds_dwordx4 v[222:223], off
	s_add_i32 m0, s72, 0x2000
	v_lshl_add_u64 v[224:225], s[92:93], 0, v[128:129]
	s_add_u32 s92, s92, s10
	s_addc_u32 s93, s93, s11
	s_add_i32 s48, s64, s8
	global_load_lds_dwordx4 v[224:225], off
	v_lshl_add_u64 v[226:227], s[92:93], 0, v[132:133]
	s_mov_b32 m0, s48
	v_lshl_add_u64 v[228:229], s[92:93], 0, v[128:129]
	global_load_lds_dwordx4 v[226:227], off
	s_add_i32 m0, s48, 0x2000
	v_lshl_add_u64 v[230:231], s[90:91], 0, v[134:135]
	global_load_lds_dwordx4 v[228:229], off
	s_mov_b32 m0, s3
	v_lshl_add_u64 v[232:233], s[90:91], 0, v[130:131]
	global_load_lds_dwordx4 v[230:231], off
	s_mov_b32 m0, s14
	s_nop 0
	global_load_lds_dwordx4 v[232:233], off
	s_waitcnt vmcnt(8)
	s_waitcnt lgkmcnt(0)
	s_barrier
	s_setprio 1
	v_mfma_f32_16x16x32_bf16 v[60:63], v[152:155], v[184:187], v[60:63]
	v_mfma_f32_16x16x32_bf16 v[56:59], v[160:163], v[184:187], v[56:59]
	v_mfma_f32_16x16x32_bf16 v[44:47], v[152:155], v[192:195], v[44:47]
	v_mfma_f32_16x16x32_bf16 v[40:43], v[160:163], v[192:195], v[40:43]
	v_mfma_f32_16x16x32_bf16 v[28:31], v[152:155], v[206:209], v[28:31]
	v_mfma_f32_16x16x32_bf16 v[24:27], v[160:163], v[206:209], v[24:27]
	v_mfma_f32_16x16x32_bf16 v[12:15], v[152:155], v[214:217], v[12:15]
	v_mfma_f32_16x16x32_bf16 v[8:11], v[160:163], v[214:217], v[8:11]
	v_mfma_f32_16x16x32_bf16 v[60:63], v[156:159], v[188:191], v[60:63]
	v_mfma_f32_16x16x32_bf16 v[56:59], v[164:167], v[188:191], v[56:59]
	v_mfma_f32_16x16x32_bf16 v[44:47], v[156:159], v[202:205], v[44:47]
	v_mfma_f32_16x16x32_bf16 v[40:43], v[164:167], v[202:205], v[40:43]
	v_mfma_f32_16x16x32_bf16 v[28:31], v[156:159], v[210:213], v[28:31]
	v_mfma_f32_16x16x32_bf16 v[24:27], v[164:167], v[210:213], v[24:27]
	v_mfma_f32_16x16x32_bf16 v[12:15], v[156:159], v[218:221], v[12:15]
	v_mfma_f32_16x16x32_bf16 v[8:11], v[164:167], v[218:221], v[8:11]
	v_mfma_f32_16x16x32_bf16 v[52:55], v[168:171], v[184:187], v[52:55]
	v_mfma_f32_16x16x32_bf16 v[48:51], v[176:179], v[184:187], v[48:51]
	v_mfma_f32_16x16x32_bf16 v[36:39], v[168:171], v[192:195], v[36:39]
	v_mfma_f32_16x16x32_bf16 v[32:35], v[176:179], v[192:195], v[32:35]
	v_mfma_f32_16x16x32_bf16 v[20:23], v[168:171], v[206:209], v[20:23]
	v_mfma_f32_16x16x32_bf16 v[16:19], v[176:179], v[206:209], v[16:19]
	v_mfma_f32_16x16x32_bf16 v[4:7], v[168:171], v[214:217], v[4:7]
	v_mfma_f32_16x16x32_bf16 v[0:3], v[176:179], v[214:217], v[0:3]
	v_mfma_f32_16x16x32_bf16 v[52:55], v[172:175], v[188:191], v[52:55]
	v_mfma_f32_16x16x32_bf16 v[48:51], v[180:183], v[188:191], v[48:51]
	v_mfma_f32_16x16x32_bf16 v[36:39], v[172:175], v[202:205], v[36:39]
	v_mfma_f32_16x16x32_bf16 v[32:35], v[180:183], v[202:205], v[32:35]
	v_mfma_f32_16x16x32_bf16 v[20:23], v[172:175], v[210:213], v[20:23]
	v_mfma_f32_16x16x32_bf16 v[16:19], v[180:183], v[210:213], v[16:19]
	v_mfma_f32_16x16x32_bf16 v[4:7], v[172:175], v[218:221], v[4:7]
	v_mfma_f32_16x16x32_bf16 v[0:3], v[180:183], v[218:221], v[0:3]
	s_setprio 0
	s_barrier
	s_add_i32 s48, 0, 0x18000
	v_add_u32_e32 v151, s48, v147
	s_add_i32 s49, 0, 0x1c000
	ds_read_b128 v[152:155], v151
	ds_read_b128 v[156:159], v151 offset:1024
	ds_read_b128 v[160:163], v151 offset:2048
	ds_read_b128 v[164:167], v151 offset:3072
	v_add_u32_e32 v151, s49, v147
	ds_read_b128 v[168:171], v151
	ds_read_b128 v[172:175], v151 offset:1024
	ds_read_b128 v[176:179], v151 offset:2048
	ds_read_b128 v[180:183], v151 offset:3072
	s_add_u32 s90, s90, s10
	s_addc_u32 s91, s91, s11
	s_mov_b32 m0, s46
	v_lshl_add_u64 v[234:235], s[90:91], 0, v[134:135]
	ds_read_b128 v[184:187], v150 offset:32768
	ds_read_b128 v[188:191], v150 offset:33792
	ds_read_b128 v[192:195], v150 offset:34816
	ds_read_b128 v[202:205], v150 offset:35840
	ds_read_b128 v[206:209], v150 offset:36864
	ds_read_b128 v[210:213], v150 offset:37888
	ds_read_b128 v[214:217], v150 offset:38912
	ds_read_b128 v[218:221], v150 offset:39936
	global_load_lds_dwordx4 v[234:235], off
	v_lshl_add_u64 v[234:235], s[90:91], 0, v[130:131]
	s_mov_b32 m0, s47
	s_nop 0
	global_load_lds_dwordx4 v[234:235], off
	s_waitcnt vmcnt(8)
	s_waitcnt lgkmcnt(0)
	s_barrier
	s_setprio 1
	v_mfma_f32_16x16x32_bf16 v[124:127], v[152:155], v[184:187], v[124:127]
	v_mfma_f32_16x16x32_bf16 v[120:123], v[160:163], v[184:187], v[120:123]
	v_mfma_f32_16x16x32_bf16 v[108:111], v[152:155], v[192:195], v[108:111]
	v_mfma_f32_16x16x32_bf16 v[104:107], v[160:163], v[192:195], v[104:107]
	v_mfma_f32_16x16x32_bf16 v[92:95], v[152:155], v[206:209], v[92:95]
	v_mfma_f32_16x16x32_bf16 v[88:91], v[160:163], v[206:209], v[88:91]
	v_mfma_f32_16x16x32_bf16 v[76:79], v[152:155], v[214:217], v[76:79]
	v_mfma_f32_16x16x32_bf16 v[72:75], v[160:163], v[214:217], v[72:75]
	v_mfma_f32_16x16x32_bf16 v[124:127], v[156:159], v[188:191], v[124:127]
	v_mfma_f32_16x16x32_bf16 v[120:123], v[164:167], v[188:191], v[120:123]
	v_mfma_f32_16x16x32_bf16 v[108:111], v[156:159], v[202:205], v[108:111]
	v_mfma_f32_16x16x32_bf16 v[104:107], v[164:167], v[202:205], v[104:107]
	v_mfma_f32_16x16x32_bf16 v[92:95], v[156:159], v[210:213], v[92:95]
	v_mfma_f32_16x16x32_bf16 v[88:91], v[164:167], v[210:213], v[88:91]
	v_mfma_f32_16x16x32_bf16 v[76:79], v[156:159], v[218:221], v[76:79]
	v_mfma_f32_16x16x32_bf16 v[72:75], v[164:167], v[218:221], v[72:75]
	v_mfma_f32_16x16x32_bf16 v[116:119], v[168:171], v[184:187], v[116:119]
	v_mfma_f32_16x16x32_bf16 v[112:115], v[176:179], v[184:187], v[112:115]
	v_mfma_f32_16x16x32_bf16 v[100:103], v[168:171], v[192:195], v[100:103]
	v_mfma_f32_16x16x32_bf16 v[96:99], v[176:179], v[192:195], v[96:99]
	v_mfma_f32_16x16x32_bf16 v[84:87], v[168:171], v[206:209], v[84:87]
	v_mfma_f32_16x16x32_bf16 v[80:83], v[176:179], v[206:209], v[80:83]
	v_mfma_f32_16x16x32_bf16 v[68:71], v[168:171], v[214:217], v[68:71]
	v_mfma_f32_16x16x32_bf16 v[64:67], v[176:179], v[214:217], v[64:67]
	v_mfma_f32_16x16x32_bf16 v[116:119], v[172:175], v[188:191], v[116:119]
	v_mfma_f32_16x16x32_bf16 v[112:115], v[180:183], v[188:191], v[112:115]
	v_mfma_f32_16x16x32_bf16 v[100:103], v[172:175], v[202:205], v[100:103]
	v_mfma_f32_16x16x32_bf16 v[96:99], v[180:183], v[202:205], v[96:99]
	v_mfma_f32_16x16x32_bf16 v[84:87], v[172:175], v[210:213], v[84:87]
	v_mfma_f32_16x16x32_bf16 v[80:83], v[180:183], v[210:213], v[80:83]
	v_mfma_f32_16x16x32_bf16 v[68:71], v[172:175], v[218:221], v[68:71]
	v_mfma_f32_16x16x32_bf16 v[64:67], v[180:183], v[218:221], v[64:67]
	s_setprio 0
	s_barrier
	s_add_i32 s48, s48, s8
	v_lshl_add_u64 v[222:223], v[222:223], 0, s[82:83]
	s_mov_b32 m0, s48
	ds_read_b128 v[184:187], v150 offset:49152
	ds_read_b128 v[188:191], v150 offset:50176
	ds_read_b128 v[192:195], v150 offset:51200
	ds_read_b128 v[202:205], v150 offset:52224
	ds_read_b128 v[206:209], v150 offset:53248
	ds_read_b128 v[210:213], v150 offset:54272
	ds_read_b128 v[214:217], v150 offset:55296
	ds_read_b128 v[218:221], v150 offset:56320
	global_load_lds_dwordx4 v[222:223], off
	v_lshl_add_u64 v[222:223], v[224:225], 0, s[82:83]
	s_add_i32 m0, s48, 0x2000
	s_add_i32 s48, s49, s8
	global_load_lds_dwordx4 v[222:223], off
	v_lshl_add_u64 v[222:223], v[226:227], 0, s[82:83]
	s_mov_b32 m0, s48
	s_nop 0
	global_load_lds_dwordx4 v[222:223], off
	v_lshl_add_u64 v[222:223], v[228:229], 0, s[82:83]
	s_add_i32 m0, s48, 0x2000
	s_nop 0
	global_load_lds_dwordx4 v[222:223], off
	v_lshl_add_u64 v[222:223], v[230:231], 0, s[82:83]
	s_mov_b32 m0, s54
	s_nop 0
	global_load_lds_dwordx4 v[222:223], off
	v_lshl_add_u64 v[222:223], v[232:233], 0, s[82:83]
	s_mov_b32 m0, s55
	s_nop 0
	global_load_lds_dwordx4 v[222:223], off
	s_waitcnt vmcnt(8)
	s_waitcnt lgkmcnt(0)
	s_barrier
	s_setprio 1
	v_mfma_f32_16x16x32_bf16 v[60:63], v[152:155], v[184:187], v[60:63]
	v_mfma_f32_16x16x32_bf16 v[56:59], v[160:163], v[184:187], v[56:59]
	v_mfma_f32_16x16x32_bf16 v[44:47], v[152:155], v[192:195], v[44:47]
	v_mfma_f32_16x16x32_bf16 v[40:43], v[160:163], v[192:195], v[40:43]
	v_mfma_f32_16x16x32_bf16 v[28:31], v[152:155], v[206:209], v[28:31]
	v_mfma_f32_16x16x32_bf16 v[24:27], v[160:163], v[206:209], v[24:27]
	v_mfma_f32_16x16x32_bf16 v[12:15], v[152:155], v[214:217], v[12:15]
	v_mfma_f32_16x16x32_bf16 v[8:11], v[160:163], v[214:217], v[8:11]
	v_mfma_f32_16x16x32_bf16 v[60:63], v[156:159], v[188:191], v[60:63]
	v_mfma_f32_16x16x32_bf16 v[56:59], v[164:167], v[188:191], v[56:59]
	v_mfma_f32_16x16x32_bf16 v[44:47], v[156:159], v[202:205], v[44:47]
	v_mfma_f32_16x16x32_bf16 v[40:43], v[164:167], v[202:205], v[40:43]
	v_mfma_f32_16x16x32_bf16 v[28:31], v[156:159], v[210:213], v[28:31]
	v_mfma_f32_16x16x32_bf16 v[24:27], v[164:167], v[210:213], v[24:27]
	v_mfma_f32_16x16x32_bf16 v[12:15], v[156:159], v[218:221], v[12:15]
	v_mfma_f32_16x16x32_bf16 v[8:11], v[164:167], v[218:221], v[8:11]
	v_mfma_f32_16x16x32_bf16 v[52:55], v[168:171], v[184:187], v[52:55]
	v_mfma_f32_16x16x32_bf16 v[48:51], v[176:179], v[184:187], v[48:51]
	v_mfma_f32_16x16x32_bf16 v[36:39], v[168:171], v[192:195], v[36:39]
	v_mfma_f32_16x16x32_bf16 v[32:35], v[176:179], v[192:195], v[32:35]
	v_mfma_f32_16x16x32_bf16 v[20:23], v[168:171], v[206:209], v[20:23]
	v_mfma_f32_16x16x32_bf16 v[16:19], v[176:179], v[206:209], v[16:19]
	v_mfma_f32_16x16x32_bf16 v[4:7], v[168:171], v[214:217], v[4:7]
	v_mfma_f32_16x16x32_bf16 v[0:3], v[176:179], v[214:217], v[0:3]
	v_mfma_f32_16x16x32_bf16 v[52:55], v[172:175], v[188:191], v[52:55]
	v_mfma_f32_16x16x32_bf16 v[48:51], v[180:183], v[188:191], v[48:51]
	v_mfma_f32_16x16x32_bf16 v[36:39], v[172:175], v[202:205], v[36:39]
	v_mfma_f32_16x16x32_bf16 v[32:35], v[180:183], v[202:205], v[32:35]
	v_mfma_f32_16x16x32_bf16 v[20:23], v[172:175], v[210:213], v[20:23]
	v_mfma_f32_16x16x32_bf16 v[16:19], v[180:183], v[210:213], v[16:19]
	v_mfma_f32_16x16x32_bf16 v[4:7], v[172:175], v[218:221], v[4:7]
	v_mfma_f32_16x16x32_bf16 v[0:3], v[180:183], v[218:221], v[0:3]
	s_setprio 0
	s_barrier
	s_add_u32 s88, s88, 0x100
	s_addc_u32 s89, s89, 0
	s_add_u32 s78, s78, 0x100
	s_addc_u32 s79, s79, 0
	s_cmp_ge_i32 s81, s53
	s_mov_b32 s80, s81
	s_cbranch_scc0 .LBB0_613

.LBB0_636:
	ds_read_b128 v[128:131], v161
	ds_read_b128 v[132:135], v161 offset:1024
	ds_read_b128 v[154:157], v161 offset:2048
	ds_read_b128 v[166:169], v161 offset:3072
	ds_read_b128 v[170:173], v162
	ds_read_b128 v[174:177], v162 offset:1024
	ds_read_b128 v[178:181], v162 offset:2048
	ds_read_b128 v[182:185], v162 offset:3072
	s_add_i32 vcc_lo, s53, 2
	s_add_u32 s48, s90, 0x80
	s_addc_u32 s49, s91, 0
	s_cmp_eq_u32 s81, s53
	s_cselect_b32 s93, s1, s49
	s_cselect_b32 s92, s0, s48
	s_cselect_b32 s49, s89, s9
	s_cselect_b32 s48, s88, s8
	v_lshl_add_u64 v[194:195], s[90:91], 0, v[146:147]
	s_add_i32 m0, s73, 0xc000
	ds_read_b128 v[186:189], v163
	ds_read_b128 v[190:193], v163 offset:1024
	ds_read_b128 v[202:205], v163 offset:2048
	ds_read_b128 v[206:209], v163 offset:3072
	ds_read_b128 v[210:213], v163 offset:4096
	ds_read_b128 v[214:217], v163 offset:5120
	ds_read_b128 v[218:221], v163 offset:6144
	ds_read_b128 v[222:225], v163 offset:7168
	global_load_lds_dwordx4 v[194:195], off
	v_lshl_add_u64 v[194:195], s[90:91], 0, v[148:149]
	s_add_i32 m0, s73, 0xe000
	s_nop 0
	global_load_lds_dwordx4 v[194:195], off
	s_waitcnt vmcnt(8)
	s_waitcnt lgkmcnt(0)
	s_barrier
	s_setprio 1
	v_mfma_f32_16x16x32_bf16 v[124:127], v[128:131], v[186:189], v[124:127]
	v_mfma_f32_16x16x32_bf16 v[120:123], v[154:157], v[186:189], v[120:123]
	v_mfma_f32_16x16x32_bf16 v[108:111], v[128:131], v[202:205], v[108:111]
	v_mfma_f32_16x16x32_bf16 v[104:107], v[154:157], v[202:205], v[104:107]
	v_mfma_f32_16x16x32_bf16 v[92:95], v[128:131], v[210:213], v[92:95]
	v_mfma_f32_16x16x32_bf16 v[88:91], v[154:157], v[210:213], v[88:91]
	v_mfma_f32_16x16x32_bf16 v[76:79], v[128:131], v[218:221], v[76:79]
	v_mfma_f32_16x16x32_bf16 v[72:75], v[154:157], v[218:221], v[72:75]
	v_mfma_f32_16x16x32_bf16 v[124:127], v[132:135], v[190:193], v[124:127]
	v_mfma_f32_16x16x32_bf16 v[120:123], v[166:169], v[190:193], v[120:123]
	v_mfma_f32_16x16x32_bf16 v[108:111], v[132:135], v[206:209], v[108:111]
	v_mfma_f32_16x16x32_bf16 v[104:107], v[166:169], v[206:209], v[104:107]
	v_mfma_f32_16x16x32_bf16 v[92:95], v[132:135], v[214:217], v[92:95]
	v_mfma_f32_16x16x32_bf16 v[88:91], v[166:169], v[214:217], v[88:91]
	v_mfma_f32_16x16x32_bf16 v[76:79], v[132:135], v[222:225], v[76:79]
	v_mfma_f32_16x16x32_bf16 v[72:75], v[166:169], v[222:225], v[72:75]
	v_mfma_f32_16x16x32_bf16 v[116:119], v[170:173], v[186:189], v[116:119]
	v_mfma_f32_16x16x32_bf16 v[112:115], v[178:181], v[186:189], v[112:115]
	v_mfma_f32_16x16x32_bf16 v[100:103], v[170:173], v[202:205], v[100:103]
	v_mfma_f32_16x16x32_bf16 v[96:99], v[178:181], v[202:205], v[96:99]
	v_mfma_f32_16x16x32_bf16 v[84:87], v[170:173], v[210:213], v[84:87]
	v_mfma_f32_16x16x32_bf16 v[80:83], v[178:181], v[210:213], v[80:83]
	v_mfma_f32_16x16x32_bf16 v[68:71], v[170:173], v[218:221], v[68:71]
	v_mfma_f32_16x16x32_bf16 v[64:67], v[178:181], v[218:221], v[64:67]
	v_mfma_f32_16x16x32_bf16 v[116:119], v[174:177], v[190:193], v[116:119]
	v_mfma_f32_16x16x32_bf16 v[112:115], v[182:185], v[190:193], v[112:115]
	v_mfma_f32_16x16x32_bf16 v[100:103], v[174:177], v[206:209], v[100:103]
	v_mfma_f32_16x16x32_bf16 v[96:99], v[182:185], v[206:209], v[96:99]
	v_mfma_f32_16x16x32_bf16 v[84:87], v[174:177], v[214:217], v[84:87]
	v_mfma_f32_16x16x32_bf16 v[80:83], v[182:185], v[214:217], v[80:83]
	v_mfma_f32_16x16x32_bf16 v[68:71], v[174:177], v[222:225], v[68:71]
	v_mfma_f32_16x16x32_bf16 v[64:67], v[182:185], v[222:225], v[64:67]
	s_setprio 0
	s_barrier
	s_add_i32 s53, s3, s65
	v_lshl_add_u64 v[194:195], s[48:49], 0, v[138:139]
	s_mov_b32 m0, s53
	ds_read_b128 v[186:189], v163 offset:16384
	ds_read_b128 v[190:193], v163 offset:17408
	ds_read_b128 v[202:205], v163 offset:18432
	ds_read_b128 v[206:209], v163 offset:19456
	ds_read_b128 v[210:213], v163 offset:20480
	ds_read_b128 v[214:217], v163 offset:21504
	ds_read_b128 v[218:221], v163 offset:22528
	ds_read_b128 v[222:225], v163 offset:23552
	global_load_lds_dwordx4 v[194:195], off
	s_add_i32 m0, s53, 0x2000
	v_lshl_add_u64 v[226:227], s[48:49], 0, v[142:143]
	s_add_u32 s48, s48, s6
	s_addc_u32 s49, s49, s7
	s_add_i32 s53, s54, s65
	global_load_lds_dwordx4 v[226:227], off
	v_lshl_add_u64 v[228:229], s[48:49], 0, v[138:139]
	s_mov_b32 m0, s53
	v_lshl_add_u64 v[230:231], s[48:49], 0, v[142:143]
	global_load_lds_dwordx4 v[228:229], off
	s_add_i32 m0, s53, 0x2000
	v_lshl_add_u64 v[232:233], s[92:93], 0, v[136:137]
	global_load_lds_dwordx4 v[230:231], off
	s_mov_b32 m0, s73
	v_lshl_add_u64 v[234:235], s[92:93], 0, v[140:141]
	global_load_lds_dwordx4 v[232:233], off
	s_mov_b32 m0, s75
	s_nop 0
	global_load_lds_dwordx4 v[234:235], off
	s_waitcnt vmcnt(8)
	s_waitcnt lgkmcnt(0)
	s_barrier
	s_setprio 1
	v_mfma_f32_16x16x32_bf16 v[60:63], v[128:131], v[186:189], v[60:63]
	v_mfma_f32_16x16x32_bf16 v[56:59], v[154:157], v[186:189], v[56:59]
	v_mfma_f32_16x16x32_bf16 v[44:47], v[128:131], v[202:205], v[44:47]
	v_mfma_f32_16x16x32_bf16 v[40:43], v[154:157], v[202:205], v[40:43]
	v_mfma_f32_16x16x32_bf16 v[28:31], v[128:131], v[210:213], v[28:31]
	v_mfma_f32_16x16x32_bf16 v[24:27], v[154:157], v[210:213], v[24:27]
	v_mfma_f32_16x16x32_bf16 v[12:15], v[128:131], v[218:221], v[12:15]
	v_mfma_f32_16x16x32_bf16 v[8:11], v[154:157], v[218:221], v[8:11]
	v_mfma_f32_16x16x32_bf16 v[60:63], v[132:135], v[190:193], v[60:63]
	v_mfma_f32_16x16x32_bf16 v[56:59], v[166:169], v[190:193], v[56:59]
	v_mfma_f32_16x16x32_bf16 v[44:47], v[132:135], v[206:209], v[44:47]
	v_mfma_f32_16x16x32_bf16 v[40:43], v[166:169], v[206:209], v[40:43]
	v_mfma_f32_16x16x32_bf16 v[28:31], v[132:135], v[214:217], v[28:31]
	v_mfma_f32_16x16x32_bf16 v[24:27], v[166:169], v[214:217], v[24:27]
	v_mfma_f32_16x16x32_bf16 v[12:15], v[132:135], v[222:225], v[12:15]
	v_mfma_f32_16x16x32_bf16 v[8:11], v[166:169], v[222:225], v[8:11]
	v_mfma_f32_16x16x32_bf16 v[52:55], v[170:173], v[186:189], v[52:55]
	v_mfma_f32_16x16x32_bf16 v[48:51], v[178:181], v[186:189], v[48:51]
	v_mfma_f32_16x16x32_bf16 v[36:39], v[170:173], v[202:205], v[36:39]
	v_mfma_f32_16x16x32_bf16 v[32:35], v[178:181], v[202:205], v[32:35]
	v_mfma_f32_16x16x32_bf16 v[20:23], v[170:173], v[210:213], v[20:23]
	v_mfma_f32_16x16x32_bf16 v[16:19], v[178:181], v[210:213], v[16:19]
	v_mfma_f32_16x16x32_bf16 v[4:7], v[170:173], v[218:221], v[4:7]
	v_mfma_f32_16x16x32_bf16 v[0:3], v[178:181], v[218:221], v[0:3]
	v_mfma_f32_16x16x32_bf16 v[52:55], v[174:177], v[190:193], v[52:55]
	v_mfma_f32_16x16x32_bf16 v[48:51], v[182:185], v[190:193], v[48:51]
	v_mfma_f32_16x16x32_bf16 v[36:39], v[174:177], v[206:209], v[36:39]
	v_mfma_f32_16x16x32_bf16 v[32:35], v[182:185], v[206:209], v[32:35]
	v_mfma_f32_16x16x32_bf16 v[20:23], v[174:177], v[214:217], v[20:23]
	v_mfma_f32_16x16x32_bf16 v[16:19], v[182:185], v[214:217], v[16:19]
	v_mfma_f32_16x16x32_bf16 v[4:7], v[174:177], v[222:225], v[4:7]
	v_mfma_f32_16x16x32_bf16 v[0:3], v[182:185], v[222:225], v[0:3]
	s_setprio 0
	s_barrier
	s_add_i32 s53, 0, 0x18000
	v_add_u32_e32 v144, s53, v160
	s_add_i32 vcc_hi, 0, 0x1c000
	ds_read_b128 v[128:131], v144
	ds_read_b128 v[132:135], v144 offset:1024
	ds_read_b128 v[154:157], v144 offset:2048
	ds_read_b128 v[166:169], v144 offset:3072
	v_add_u32_e32 v144, vcc_hi, v160
	ds_read_b128 v[170:173], v144
	ds_read_b128 v[174:177], v144 offset:1024
	ds_read_b128 v[178:181], v144 offset:2048
	ds_read_b128 v[182:185], v144 offset:3072
	s_add_u32 s48, s92, s6
	s_addc_u32 s49, s93, s7
	s_mov_b32 m0, s77
	v_lshl_add_u64 v[236:237], s[48:49], 0, v[136:137]
	ds_read_b128 v[186:189], v163 offset:32768
	ds_read_b128 v[190:193], v163 offset:33792
	ds_read_b128 v[202:205], v163 offset:34816
	ds_read_b128 v[206:209], v163 offset:35840
	ds_read_b128 v[210:213], v163 offset:36864
	ds_read_b128 v[214:217], v163 offset:37888
	ds_read_b128 v[218:221], v163 offset:38912
	ds_read_b128 v[222:225], v163 offset:39936
	global_load_lds_dwordx4 v[236:237], off
	v_lshl_add_u64 v[236:237], s[48:49], 0, v[140:141]
	s_mov_b32 m0, s78
	s_nop 0
	global_load_lds_dwordx4 v[236:237], off
	s_waitcnt vmcnt(8)
	s_waitcnt lgkmcnt(0)
	s_barrier
	s_setprio 1
	v_mfma_f32_16x16x32_bf16 v[124:127], v[128:131], v[186:189], v[124:127]
	v_mfma_f32_16x16x32_bf16 v[120:123], v[154:157], v[186:189], v[120:123]
	v_mfma_f32_16x16x32_bf16 v[108:111], v[128:131], v[202:205], v[108:111]
	v_mfma_f32_16x16x32_bf16 v[104:107], v[154:157], v[202:205], v[104:107]
	v_mfma_f32_16x16x32_bf16 v[92:95], v[128:131], v[210:213], v[92:95]
	v_mfma_f32_16x16x32_bf16 v[88:91], v[154:157], v[210:213], v[88:91]
	v_mfma_f32_16x16x32_bf16 v[76:79], v[128:131], v[218:221], v[76:79]
	v_mfma_f32_16x16x32_bf16 v[72:75], v[154:157], v[218:221], v[72:75]
	v_mfma_f32_16x16x32_bf16 v[124:127], v[132:135], v[190:193], v[124:127]
	v_mfma_f32_16x16x32_bf16 v[120:123], v[166:169], v[190:193], v[120:123]
	v_mfma_f32_16x16x32_bf16 v[108:111], v[132:135], v[206:209], v[108:111]
	v_mfma_f32_16x16x32_bf16 v[104:107], v[166:169], v[206:209], v[104:107]
	v_mfma_f32_16x16x32_bf16 v[92:95], v[132:135], v[214:217], v[92:95]
	v_mfma_f32_16x16x32_bf16 v[88:91], v[166:169], v[214:217], v[88:91]
	v_mfma_f32_16x16x32_bf16 v[76:79], v[132:135], v[222:225], v[76:79]
	v_mfma_f32_16x16x32_bf16 v[72:75], v[166:169], v[222:225], v[72:75]
	v_mfma_f32_16x16x32_bf16 v[116:119], v[170:173], v[186:189], v[116:119]
	v_mfma_f32_16x16x32_bf16 v[112:115], v[178:181], v[186:189], v[112:115]
	v_mfma_f32_16x16x32_bf16 v[100:103], v[170:173], v[202:205], v[100:103]
	v_mfma_f32_16x16x32_bf16 v[96:99], v[178:181], v[202:205], v[96:99]
	v_mfma_f32_16x16x32_bf16 v[84:87], v[170:173], v[210:213], v[84:87]
	v_mfma_f32_16x16x32_bf16 v[80:83], v[178:181], v[210:213], v[80:83]
	v_mfma_f32_16x16x32_bf16 v[68:71], v[170:173], v[218:221], v[68:71]
	v_mfma_f32_16x16x32_bf16 v[64:67], v[178:181], v[218:221], v[64:67]
	v_mfma_f32_16x16x32_bf16 v[116:119], v[174:177], v[190:193], v[116:119]
	v_mfma_f32_16x16x32_bf16 v[112:115], v[182:185], v[190:193], v[112:115]
	v_mfma_f32_16x16x32_bf16 v[100:103], v[174:177], v[206:209], v[100:103]
	v_mfma_f32_16x16x32_bf16 v[96:99], v[182:185], v[206:209], v[96:99]
	v_mfma_f32_16x16x32_bf16 v[84:87], v[174:177], v[214:217], v[84:87]
	v_mfma_f32_16x16x32_bf16 v[80:83], v[182:185], v[214:217], v[80:83]
	v_mfma_f32_16x16x32_bf16 v[68:71], v[174:177], v[222:225], v[68:71]
	v_mfma_f32_16x16x32_bf16 v[64:67], v[182:185], v[222:225], v[64:67]
	s_setprio 0
	s_barrier
	s_add_i32 s48, s53, s65
	v_lshl_add_u64 v[194:195], v[194:195], 0, s[82:83]
	s_mov_b32 m0, s48
	ds_read_b128 v[186:189], v163 offset:49152
	ds_read_b128 v[190:193], v163 offset:50176
	ds_read_b128 v[202:205], v163 offset:51200
	ds_read_b128 v[206:209], v163 offset:52224
	ds_read_b128 v[210:213], v163 offset:53248
	ds_read_b128 v[214:217], v163 offset:54272
	ds_read_b128 v[218:221], v163 offset:55296
	ds_read_b128 v[222:225], v163 offset:56320
	global_load_lds_dwordx4 v[194:195], off
	v_lshl_add_u64 v[194:195], v[226:227], 0, s[82:83]
	s_add_i32 m0, s48, 0x2000
	s_add_i32 s48, vcc_hi, s65
	global_load_lds_dwordx4 v[194:195], off
	v_lshl_add_u64 v[194:195], v[228:229], 0, s[82:83]
	s_mov_b32 m0, s48
	s_nop 0
	global_load_lds_dwordx4 v[194:195], off
	v_lshl_add_u64 v[194:195], v[230:231], 0, s[82:83]
	s_add_i32 m0, s48, 0x2000
	s_nop 0
	global_load_lds_dwordx4 v[194:195], off
	v_lshl_add_u64 v[194:195], v[232:233], 0, s[82:83]
	s_mov_b32 m0, s96
	s_nop 0
	global_load_lds_dwordx4 v[194:195], off
	v_lshl_add_u64 v[194:195], v[234:235], 0, s[82:83]
	s_mov_b32 m0, s97
	s_nop 0
	global_load_lds_dwordx4 v[194:195], off
	s_waitcnt vmcnt(8)
	s_waitcnt lgkmcnt(0)
	s_barrier
	s_setprio 1
	v_mfma_f32_16x16x32_bf16 v[60:63], v[128:131], v[186:189], v[60:63]
	v_mfma_f32_16x16x32_bf16 v[56:59], v[154:157], v[186:189], v[56:59]
	v_mfma_f32_16x16x32_bf16 v[44:47], v[128:131], v[202:205], v[44:47]
	v_mfma_f32_16x16x32_bf16 v[40:43], v[154:157], v[202:205], v[40:43]
	v_mfma_f32_16x16x32_bf16 v[28:31], v[128:131], v[210:213], v[28:31]
	v_mfma_f32_16x16x32_bf16 v[24:27], v[154:157], v[210:213], v[24:27]
	v_mfma_f32_16x16x32_bf16 v[12:15], v[128:131], v[218:221], v[12:15]
	v_mfma_f32_16x16x32_bf16 v[8:11], v[154:157], v[218:221], v[8:11]
	v_mfma_f32_16x16x32_bf16 v[60:63], v[132:135], v[190:193], v[60:63]
	v_mfma_f32_16x16x32_bf16 v[56:59], v[166:169], v[190:193], v[56:59]
	v_mfma_f32_16x16x32_bf16 v[44:47], v[132:135], v[206:209], v[44:47]
	v_mfma_f32_16x16x32_bf16 v[40:43], v[166:169], v[206:209], v[40:43]
	v_mfma_f32_16x16x32_bf16 v[28:31], v[132:135], v[214:217], v[28:31]
	v_mfma_f32_16x16x32_bf16 v[24:27], v[166:169], v[214:217], v[24:27]
	v_mfma_f32_16x16x32_bf16 v[12:15], v[132:135], v[222:225], v[12:15]
	v_mfma_f32_16x16x32_bf16 v[8:11], v[166:169], v[222:225], v[8:11]
	v_mfma_f32_16x16x32_bf16 v[52:55], v[170:173], v[186:189], v[52:55]
	v_mfma_f32_16x16x32_bf16 v[48:51], v[178:181], v[186:189], v[48:51]
	v_mfma_f32_16x16x32_bf16 v[36:39], v[170:173], v[202:205], v[36:39]
	v_mfma_f32_16x16x32_bf16 v[32:35], v[178:181], v[202:205], v[32:35]
	v_mfma_f32_16x16x32_bf16 v[20:23], v[170:173], v[210:213], v[20:23]
	v_mfma_f32_16x16x32_bf16 v[16:19], v[178:181], v[210:213], v[16:19]
	v_mfma_f32_16x16x32_bf16 v[4:7], v[170:173], v[218:221], v[4:7]
	v_mfma_f32_16x16x32_bf16 v[0:3], v[178:181], v[218:221], v[0:3]
	v_mfma_f32_16x16x32_bf16 v[52:55], v[174:177], v[190:193], v[52:55]
	v_mfma_f32_16x16x32_bf16 v[48:51], v[182:185], v[190:193], v[48:51]
	v_mfma_f32_16x16x32_bf16 v[36:39], v[174:177], v[206:209], v[36:39]
	v_mfma_f32_16x16x32_bf16 v[32:35], v[182:185], v[206:209], v[32:35]
	v_mfma_f32_16x16x32_bf16 v[20:23], v[174:177], v[214:217], v[20:23]
	v_mfma_f32_16x16x32_bf16 v[16:19], v[182:185], v[214:217], v[16:19]
	v_mfma_f32_16x16x32_bf16 v[4:7], v[174:177], v[222:225], v[4:7]
	v_mfma_f32_16x16x32_bf16 v[0:3], v[182:185], v[222:225], v[0:3]
	s_setprio 0
	s_barrier
	s_add_u32 s90, s90, 0x100
	s_addc_u32 s91, s91, 0
	s_add_u32 s8, s8, 0x100
	s_addc_u32 s9, s9, 0
	s_cmp_ge_i32 vcc_lo, s70
	s_mov_b32 s53, vcc_lo
	s_cbranch_scc0 .LBB0_636

.LBB0_727:
	ds_read_b128 v[148:151], v155
	ds_read_b128 v[160:163], v155 offset:1024
	ds_read_b128 v[164:167], v155 offset:2048
	ds_read_b128 v[168:171], v155 offset:3072
	ds_read_b128 v[172:175], v156
	ds_read_b128 v[176:179], v156 offset:1024
	ds_read_b128 v[180:183], v156 offset:2048
	ds_read_b128 v[184:187], v156 offset:3072
	s_add_i32 s92, s88, 2
	s_add_u32 s48, s86, 0x80
	s_addc_u32 s49, s87, 0
	s_cmp_eq_u32 s73, s88
	s_cselect_b32 s88, s4, s48
	s_cselect_b32 s89, s5, s49
	s_cselect_b32 s49, s85, s91
	s_cselect_b32 s48, s84, s90
	s_mov_b32 m0, s79
	v_lshl_add_u64 v[226:227], s[86:87], 0, v[140:141]
	ds_read_b128 v[188:191], v157
	ds_read_b128 v[192:195], v157 offset:1024
	ds_read_b128 v[202:205], v157 offset:2048
	ds_read_b128 v[206:209], v157 offset:3072
	ds_read_b128 v[210:213], v157 offset:4096
	ds_read_b128 v[214:217], v157 offset:5120
	ds_read_b128 v[218:221], v157 offset:6144
	ds_read_b128 v[222:225], v157 offset:7168
	global_load_lds_dwordx4 v[226:227], off
	v_lshl_add_u64 v[226:227], s[86:87], 0, v[142:143]
	s_add_i32 m0, s52, 0xe000
	s_nop 0
	global_load_lds_dwordx4 v[226:227], off
	s_waitcnt vmcnt(8)
	s_waitcnt lgkmcnt(0)
	s_barrier
	s_setprio 1
	v_mfma_f32_16x16x32_bf16 v[124:127], v[148:151], v[188:191], v[124:127]
	v_mfma_f32_16x16x32_bf16 v[120:123], v[164:167], v[188:191], v[120:123]
	v_mfma_f32_16x16x32_bf16 v[108:111], v[148:151], v[202:205], v[108:111]
	v_mfma_f32_16x16x32_bf16 v[104:107], v[164:167], v[202:205], v[104:107]
	v_mfma_f32_16x16x32_bf16 v[92:95], v[148:151], v[210:213], v[92:95]
	v_mfma_f32_16x16x32_bf16 v[88:91], v[164:167], v[210:213], v[88:91]
	v_mfma_f32_16x16x32_bf16 v[76:79], v[148:151], v[218:221], v[76:79]
	v_mfma_f32_16x16x32_bf16 v[72:75], v[164:167], v[218:221], v[72:75]
	v_mfma_f32_16x16x32_bf16 v[124:127], v[160:163], v[192:195], v[124:127]
	v_mfma_f32_16x16x32_bf16 v[120:123], v[168:171], v[192:195], v[120:123]
	v_mfma_f32_16x16x32_bf16 v[108:111], v[160:163], v[206:209], v[108:111]
	v_mfma_f32_16x16x32_bf16 v[104:107], v[168:171], v[206:209], v[104:107]
	v_mfma_f32_16x16x32_bf16 v[92:95], v[160:163], v[214:217], v[92:95]
	v_mfma_f32_16x16x32_bf16 v[88:91], v[168:171], v[214:217], v[88:91]
	v_mfma_f32_16x16x32_bf16 v[76:79], v[160:163], v[222:225], v[76:79]
	v_mfma_f32_16x16x32_bf16 v[72:75], v[168:171], v[222:225], v[72:75]
	v_mfma_f32_16x16x32_bf16 v[116:119], v[172:175], v[188:191], v[116:119]
	v_mfma_f32_16x16x32_bf16 v[112:115], v[180:183], v[188:191], v[112:115]
	v_mfma_f32_16x16x32_bf16 v[100:103], v[172:175], v[202:205], v[100:103]
	v_mfma_f32_16x16x32_bf16 v[96:99], v[180:183], v[202:205], v[96:99]
	v_mfma_f32_16x16x32_bf16 v[84:87], v[172:175], v[210:213], v[84:87]
	v_mfma_f32_16x16x32_bf16 v[80:83], v[180:183], v[210:213], v[80:83]
	v_mfma_f32_16x16x32_bf16 v[68:71], v[172:175], v[218:221], v[68:71]
	v_mfma_f32_16x16x32_bf16 v[64:67], v[180:183], v[218:221], v[64:67]
	v_mfma_f32_16x16x32_bf16 v[116:119], v[176:179], v[192:195], v[116:119]
	v_mfma_f32_16x16x32_bf16 v[112:115], v[184:187], v[192:195], v[112:115]
	v_mfma_f32_16x16x32_bf16 v[100:103], v[176:179], v[206:209], v[100:103]
	v_mfma_f32_16x16x32_bf16 v[96:99], v[184:187], v[206:209], v[96:99]
	v_mfma_f32_16x16x32_bf16 v[84:87], v[176:179], v[214:217], v[84:87]
	v_mfma_f32_16x16x32_bf16 v[80:83], v[184:187], v[214:217], v[80:83]
	v_mfma_f32_16x16x32_bf16 v[68:71], v[176:179], v[222:225], v[68:71]
	v_mfma_f32_16x16x32_bf16 v[64:67], v[184:187], v[222:225], v[64:67]
	s_setprio 0
	s_barrier
	s_add_i32 s93, s75, s14
	v_lshl_add_u64 v[226:227], s[48:49], 0, v[132:133]
	s_mov_b32 m0, s93
	ds_read_b128 v[188:191], v157 offset:16384
	ds_read_b128 v[192:195], v157 offset:17408
	ds_read_b128 v[202:205], v157 offset:18432
	ds_read_b128 v[206:209], v157 offset:19456
	ds_read_b128 v[210:213], v157 offset:20480
	ds_read_b128 v[214:217], v157 offset:21504
	ds_read_b128 v[218:221], v157 offset:22528
	ds_read_b128 v[222:225], v157 offset:23552
	global_load_lds_dwordx4 v[226:227], off
	s_add_i32 m0, s93, 0x2000
	v_lshl_add_u64 v[228:229], s[48:49], 0, v[128:129]
	s_add_u32 s48, s48, s10
	s_addc_u32 s49, s49, s11
	s_add_i32 s93, s77, s14
	global_load_lds_dwordx4 v[228:229], off
	v_lshl_add_u64 v[230:231], s[48:49], 0, v[132:133]
	s_mov_b32 m0, s93
	v_lshl_add_u64 v[232:233], s[48:49], 0, v[128:129]
	global_load_lds_dwordx4 v[230:231], off
	s_add_i32 m0, s93, 0x2000
	v_lshl_add_u64 v[234:235], s[88:89], 0, v[134:135]
	global_load_lds_dwordx4 v[232:233], off
	s_mov_b32 m0, s52
	v_lshl_add_u64 v[236:237], s[88:89], 0, v[130:131]
	global_load_lds_dwordx4 v[234:235], off
	s_mov_b32 m0, s53
	s_nop 0
	global_load_lds_dwordx4 v[236:237], off
	s_waitcnt vmcnt(8)
	s_waitcnt lgkmcnt(0)
	s_barrier
	s_setprio 1
	v_mfma_f32_16x16x32_bf16 v[60:63], v[148:151], v[188:191], v[60:63]
	v_mfma_f32_16x16x32_bf16 v[56:59], v[164:167], v[188:191], v[56:59]
	v_mfma_f32_16x16x32_bf16 v[44:47], v[148:151], v[202:205], v[44:47]
	v_mfma_f32_16x16x32_bf16 v[40:43], v[164:167], v[202:205], v[40:43]
	v_mfma_f32_16x16x32_bf16 v[28:31], v[148:151], v[210:213], v[28:31]
	v_mfma_f32_16x16x32_bf16 v[24:27], v[164:167], v[210:213], v[24:27]
	v_mfma_f32_16x16x32_bf16 v[12:15], v[148:151], v[218:221], v[12:15]
	v_mfma_f32_16x16x32_bf16 v[8:11], v[164:167], v[218:221], v[8:11]
	v_mfma_f32_16x16x32_bf16 v[60:63], v[160:163], v[192:195], v[60:63]
	v_mfma_f32_16x16x32_bf16 v[56:59], v[168:171], v[192:195], v[56:59]
	v_mfma_f32_16x16x32_bf16 v[44:47], v[160:163], v[206:209], v[44:47]
	v_mfma_f32_16x16x32_bf16 v[40:43], v[168:171], v[206:209], v[40:43]
	v_mfma_f32_16x16x32_bf16 v[28:31], v[160:163], v[214:217], v[28:31]
	v_mfma_f32_16x16x32_bf16 v[24:27], v[168:171], v[214:217], v[24:27]
	v_mfma_f32_16x16x32_bf16 v[12:15], v[160:163], v[222:225], v[12:15]
	v_mfma_f32_16x16x32_bf16 v[8:11], v[168:171], v[222:225], v[8:11]
	v_mfma_f32_16x16x32_bf16 v[52:55], v[172:175], v[188:191], v[52:55]
	v_mfma_f32_16x16x32_bf16 v[48:51], v[180:183], v[188:191], v[48:51]
	v_mfma_f32_16x16x32_bf16 v[36:39], v[172:175], v[202:205], v[36:39]
	v_mfma_f32_16x16x32_bf16 v[32:35], v[180:183], v[202:205], v[32:35]
	v_mfma_f32_16x16x32_bf16 v[20:23], v[172:175], v[210:213], v[20:23]
	v_mfma_f32_16x16x32_bf16 v[16:19], v[180:183], v[210:213], v[16:19]
	v_mfma_f32_16x16x32_bf16 v[4:7], v[172:175], v[218:221], v[4:7]
	v_mfma_f32_16x16x32_bf16 v[0:3], v[180:183], v[218:221], v[0:3]
	v_mfma_f32_16x16x32_bf16 v[52:55], v[176:179], v[192:195], v[52:55]
	v_mfma_f32_16x16x32_bf16 v[48:51], v[184:187], v[192:195], v[48:51]
	v_mfma_f32_16x16x32_bf16 v[36:39], v[176:179], v[206:209], v[36:39]
	v_mfma_f32_16x16x32_bf16 v[32:35], v[184:187], v[206:209], v[32:35]
	v_mfma_f32_16x16x32_bf16 v[20:23], v[176:179], v[214:217], v[20:23]
	v_mfma_f32_16x16x32_bf16 v[16:19], v[184:187], v[214:217], v[16:19]
	v_mfma_f32_16x16x32_bf16 v[4:7], v[176:179], v[222:225], v[4:7]
	v_mfma_f32_16x16x32_bf16 v[0:3], v[184:187], v[222:225], v[0:3]
	s_setprio 0
	s_barrier
	s_add_i32 s93, 0, 0x18000
	v_add_u32_e32 v136, s93, v152
	s_add_i32 s94, 0, 0x1c000
	ds_read_b128 v[148:151], v136
	ds_read_b128 v[160:163], v136 offset:1024
	ds_read_b128 v[164:167], v136 offset:2048
	ds_read_b128 v[168:171], v136 offset:3072
	v_add_u32_e32 v136, s94, v152
	ds_read_b128 v[172:175], v136
	ds_read_b128 v[176:179], v136 offset:1024
	ds_read_b128 v[180:183], v136 offset:2048
	ds_read_b128 v[184:187], v136 offset:3072
	s_add_u32 s48, s88, s10
	s_addc_u32 s49, s89, s11
	s_mov_b32 m0, s54
	v_lshl_add_u64 v[238:239], s[48:49], 0, v[134:135]
	ds_read_b128 v[188:191], v157 offset:32768
	ds_read_b128 v[192:195], v157 offset:33792
	ds_read_b128 v[202:205], v157 offset:34816
	ds_read_b128 v[206:209], v157 offset:35840
	ds_read_b128 v[210:213], v157 offset:36864
	ds_read_b128 v[214:217], v157 offset:37888
	ds_read_b128 v[218:221], v157 offset:38912
	ds_read_b128 v[222:225], v157 offset:39936
	global_load_lds_dwordx4 v[238:239], off
	v_lshl_add_u64 v[238:239], s[48:49], 0, v[130:131]
	s_mov_b32 m0, s55
	s_nop 0
	global_load_lds_dwordx4 v[238:239], off
	s_waitcnt vmcnt(8)
	s_waitcnt lgkmcnt(0)
	s_barrier
	s_setprio 1
	v_mfma_f32_16x16x32_bf16 v[124:127], v[148:151], v[188:191], v[124:127]
	v_mfma_f32_16x16x32_bf16 v[120:123], v[164:167], v[188:191], v[120:123]
	v_mfma_f32_16x16x32_bf16 v[108:111], v[148:151], v[202:205], v[108:111]
	v_mfma_f32_16x16x32_bf16 v[104:107], v[164:167], v[202:205], v[104:107]
	v_mfma_f32_16x16x32_bf16 v[92:95], v[148:151], v[210:213], v[92:95]
	v_mfma_f32_16x16x32_bf16 v[88:91], v[164:167], v[210:213], v[88:91]
	v_mfma_f32_16x16x32_bf16 v[76:79], v[148:151], v[218:221], v[76:79]
	v_mfma_f32_16x16x32_bf16 v[72:75], v[164:167], v[218:221], v[72:75]
	v_mfma_f32_16x16x32_bf16 v[124:127], v[160:163], v[192:195], v[124:127]
	v_mfma_f32_16x16x32_bf16 v[120:123], v[168:171], v[192:195], v[120:123]
	v_mfma_f32_16x16x32_bf16 v[108:111], v[160:163], v[206:209], v[108:111]
	v_mfma_f32_16x16x32_bf16 v[104:107], v[168:171], v[206:209], v[104:107]
	v_mfma_f32_16x16x32_bf16 v[92:95], v[160:163], v[214:217], v[92:95]
	v_mfma_f32_16x16x32_bf16 v[88:91], v[168:171], v[214:217], v[88:91]
	v_mfma_f32_16x16x32_bf16 v[76:79], v[160:163], v[222:225], v[76:79]
	v_mfma_f32_16x16x32_bf16 v[72:75], v[168:171], v[222:225], v[72:75]
	v_mfma_f32_16x16x32_bf16 v[116:119], v[172:175], v[188:191], v[116:119]
	v_mfma_f32_16x16x32_bf16 v[112:115], v[180:183], v[188:191], v[112:115]
	v_mfma_f32_16x16x32_bf16 v[100:103], v[172:175], v[202:205], v[100:103]
	v_mfma_f32_16x16x32_bf16 v[96:99], v[180:183], v[202:205], v[96:99]
	v_mfma_f32_16x16x32_bf16 v[84:87], v[172:175], v[210:213], v[84:87]
	v_mfma_f32_16x16x32_bf16 v[80:83], v[180:183], v[210:213], v[80:83]
	v_mfma_f32_16x16x32_bf16 v[68:71], v[172:175], v[218:221], v[68:71]
	v_mfma_f32_16x16x32_bf16 v[64:67], v[180:183], v[218:221], v[64:67]
	v_mfma_f32_16x16x32_bf16 v[116:119], v[176:179], v[192:195], v[116:119]
	v_mfma_f32_16x16x32_bf16 v[112:115], v[184:187], v[192:195], v[112:115]
	v_mfma_f32_16x16x32_bf16 v[100:103], v[176:179], v[206:209], v[100:103]
	v_mfma_f32_16x16x32_bf16 v[96:99], v[184:187], v[206:209], v[96:99]
	v_mfma_f32_16x16x32_bf16 v[84:87], v[176:179], v[214:217], v[84:87]
	v_mfma_f32_16x16x32_bf16 v[80:83], v[184:187], v[214:217], v[80:83]
	v_mfma_f32_16x16x32_bf16 v[68:71], v[176:179], v[222:225], v[68:71]
	v_mfma_f32_16x16x32_bf16 v[64:67], v[184:187], v[222:225], v[64:67]
	s_setprio 0
	s_barrier
	s_add_i32 s48, s93, s14
	v_lshl_add_u64 v[226:227], v[226:227], 0, s[66:67]
	s_mov_b32 m0, s48
	ds_read_b128 v[188:191], v157 offset:49152
	ds_read_b128 v[192:195], v157 offset:50176
	ds_read_b128 v[202:205], v157 offset:51200
	ds_read_b128 v[206:209], v157 offset:52224
	ds_read_b128 v[210:213], v157 offset:53248
	ds_read_b128 v[214:217], v157 offset:54272
	ds_read_b128 v[218:221], v157 offset:55296
	ds_read_b128 v[222:225], v157 offset:56320
	global_load_lds_dwordx4 v[226:227], off
	v_lshl_add_u64 v[226:227], v[228:229], 0, s[66:67]
	s_add_i32 m0, s48, 0x2000
	s_add_i32 s48, s94, s14
	global_load_lds_dwordx4 v[226:227], off
	v_lshl_add_u64 v[226:227], v[230:231], 0, s[66:67]
	s_mov_b32 m0, s48
	s_nop 0
	global_load_lds_dwordx4 v[226:227], off
	v_lshl_add_u64 v[226:227], v[232:233], 0, s[66:67]
	s_add_i32 m0, s48, 0x2000
	s_nop 0
	global_load_lds_dwordx4 v[226:227], off
	v_lshl_add_u64 v[226:227], v[234:235], 0, s[66:67]
	s_mov_b32 m0, s70
	s_nop 0
	global_load_lds_dwordx4 v[226:227], off
	v_lshl_add_u64 v[226:227], v[236:237], 0, s[66:67]
	s_mov_b32 m0, s71
	s_nop 0
	global_load_lds_dwordx4 v[226:227], off
	s_waitcnt vmcnt(8)
	s_waitcnt lgkmcnt(0)
	s_barrier
	s_setprio 1
	v_mfma_f32_16x16x32_bf16 v[60:63], v[148:151], v[188:191], v[60:63]
	v_mfma_f32_16x16x32_bf16 v[56:59], v[164:167], v[188:191], v[56:59]
	v_mfma_f32_16x16x32_bf16 v[44:47], v[148:151], v[202:205], v[44:47]
	v_mfma_f32_16x16x32_bf16 v[40:43], v[164:167], v[202:205], v[40:43]
	v_mfma_f32_16x16x32_bf16 v[28:31], v[148:151], v[210:213], v[28:31]
	v_mfma_f32_16x16x32_bf16 v[24:27], v[164:167], v[210:213], v[24:27]
	v_mfma_f32_16x16x32_bf16 v[12:15], v[148:151], v[218:221], v[12:15]
	v_mfma_f32_16x16x32_bf16 v[8:11], v[164:167], v[218:221], v[8:11]
	v_mfma_f32_16x16x32_bf16 v[60:63], v[160:163], v[192:195], v[60:63]
	v_mfma_f32_16x16x32_bf16 v[56:59], v[168:171], v[192:195], v[56:59]
	v_mfma_f32_16x16x32_bf16 v[44:47], v[160:163], v[206:209], v[44:47]
	v_mfma_f32_16x16x32_bf16 v[40:43], v[168:171], v[206:209], v[40:43]
	v_mfma_f32_16x16x32_bf16 v[28:31], v[160:163], v[214:217], v[28:31]
	v_mfma_f32_16x16x32_bf16 v[24:27], v[168:171], v[214:217], v[24:27]
	v_mfma_f32_16x16x32_bf16 v[12:15], v[160:163], v[222:225], v[12:15]
	v_mfma_f32_16x16x32_bf16 v[8:11], v[168:171], v[222:225], v[8:11]
	v_mfma_f32_16x16x32_bf16 v[52:55], v[172:175], v[188:191], v[52:55]
	v_mfma_f32_16x16x32_bf16 v[48:51], v[180:183], v[188:191], v[48:51]
	v_mfma_f32_16x16x32_bf16 v[36:39], v[172:175], v[202:205], v[36:39]
	v_mfma_f32_16x16x32_bf16 v[32:35], v[180:183], v[202:205], v[32:35]
	v_mfma_f32_16x16x32_bf16 v[20:23], v[172:175], v[210:213], v[20:23]
	v_mfma_f32_16x16x32_bf16 v[16:19], v[180:183], v[210:213], v[16:19]
	v_mfma_f32_16x16x32_bf16 v[4:7], v[172:175], v[218:221], v[4:7]
	v_mfma_f32_16x16x32_bf16 v[0:3], v[180:183], v[218:221], v[0:3]
	v_mfma_f32_16x16x32_bf16 v[52:55], v[176:179], v[192:195], v[52:55]
	v_mfma_f32_16x16x32_bf16 v[48:51], v[184:187], v[192:195], v[48:51]
	v_mfma_f32_16x16x32_bf16 v[36:39], v[176:179], v[206:209], v[36:39]
	v_mfma_f32_16x16x32_bf16 v[32:35], v[184:187], v[206:209], v[32:35]
	v_mfma_f32_16x16x32_bf16 v[20:23], v[176:179], v[214:217], v[20:23]
	v_mfma_f32_16x16x32_bf16 v[16:19], v[184:187], v[214:217], v[16:19]
	v_mfma_f32_16x16x32_bf16 v[4:7], v[176:179], v[222:225], v[4:7]
	v_mfma_f32_16x16x32_bf16 v[0:3], v[184:187], v[222:225], v[0:3]
	s_setprio 0
	s_barrier
	s_add_u32 s86, s86, 0x100
	s_addc_u32 s87, s87, 0
	s_add_u32 s90, s90, 0x100
	s_addc_u32 s91, s91, 0
	s_cmp_ge_i32 s92, s64
	s_mov_b32 s88, s92
	s_cbranch_scc0 .LBB0_727

.LBB0_966:
	ds_read_b128 v[146:149], v151
	ds_read_b128 v[154:157], v151 offset:1024
	ds_read_b128 v[158:161], v151 offset:2048
	ds_read_b128 v[162:165], v151 offset:3072
	ds_read_b128 v[166:169], v152
	ds_read_b128 v[170:173], v152 offset:1024
	ds_read_b128 v[174:177], v152 offset:2048
	ds_read_b128 v[178:181], v152 offset:3072
	s_add_u32 s28, s26, 0xfffc0080
	s_addc_u32 s29, s27, -1
	s_cmp_eq_u32 s63, 12
	s_cselect_b32 s53, s12, s29
	s_cselect_b32 s52, s13, s28
	s_cselect_b32 s29, s17, s62
	s_cselect_b32 s28, s19, s61
	v_lshl_add_u64 v[194:195], s[26:27], 0, v[138:139]
	s_add_i32 m0, s14, 0xc000
	ds_read_b128 v[182:185], v153
	ds_read_b128 v[186:189], v153 offset:1024
	ds_read_b128 v[190:193], v153 offset:2048
	ds_read_b128 v[198:201], v153 offset:3072
	ds_read_b128 v[202:205], v153 offset:4096
	ds_read_b128 v[206:209], v153 offset:5120
	ds_read_b128 v[210:213], v153 offset:6144
	ds_read_b128 v[214:217], v153 offset:7168
	global_load_lds_dwordx4 v[194:195], off
	v_lshl_add_u64 v[194:195], s[26:27], 0, v[140:141]
	s_add_i32 m0, s14, 0xe000
	s_nop 0
	global_load_lds_dwordx4 v[194:195], off
	s_waitcnt vmcnt(8)
	s_waitcnt lgkmcnt(0)
	s_barrier
	s_setprio 1
	v_mfma_f32_16x16x32_bf16 v[124:127], v[146:149], v[182:185], v[124:127]
	v_mfma_f32_16x16x32_bf16 v[120:123], v[158:161], v[182:185], v[120:123]
	v_mfma_f32_16x16x32_bf16 v[108:111], v[146:149], v[190:193], v[108:111]
	v_mfma_f32_16x16x32_bf16 v[104:107], v[158:161], v[190:193], v[104:107]
	v_mfma_f32_16x16x32_bf16 v[92:95], v[146:149], v[202:205], v[92:95]
	v_mfma_f32_16x16x32_bf16 v[88:91], v[158:161], v[202:205], v[88:91]
	v_mfma_f32_16x16x32_bf16 v[76:79], v[146:149], v[210:213], v[76:79]
	v_mfma_f32_16x16x32_bf16 v[72:75], v[158:161], v[210:213], v[72:75]
	v_mfma_f32_16x16x32_bf16 v[124:127], v[154:157], v[186:189], v[124:127]
	v_mfma_f32_16x16x32_bf16 v[120:123], v[162:165], v[186:189], v[120:123]
	v_mfma_f32_16x16x32_bf16 v[108:111], v[154:157], v[198:201], v[108:111]
	v_mfma_f32_16x16x32_bf16 v[104:107], v[162:165], v[198:201], v[104:107]
	v_mfma_f32_16x16x32_bf16 v[92:95], v[154:157], v[206:209], v[92:95]
	v_mfma_f32_16x16x32_bf16 v[88:91], v[162:165], v[206:209], v[88:91]
	v_mfma_f32_16x16x32_bf16 v[76:79], v[154:157], v[214:217], v[76:79]
	v_mfma_f32_16x16x32_bf16 v[72:75], v[162:165], v[214:217], v[72:75]
	v_mfma_f32_16x16x32_bf16 v[116:119], v[166:169], v[182:185], v[116:119]
	v_mfma_f32_16x16x32_bf16 v[112:115], v[174:177], v[182:185], v[112:115]
	v_mfma_f32_16x16x32_bf16 v[100:103], v[166:169], v[190:193], v[100:103]
	v_mfma_f32_16x16x32_bf16 v[96:99], v[174:177], v[190:193], v[96:99]
	v_mfma_f32_16x16x32_bf16 v[84:87], v[166:169], v[202:205], v[84:87]
	v_mfma_f32_16x16x32_bf16 v[80:83], v[174:177], v[202:205], v[80:83]
	v_mfma_f32_16x16x32_bf16 v[68:71], v[166:169], v[210:213], v[68:71]
	v_mfma_f32_16x16x32_bf16 v[64:67], v[174:177], v[210:213], v[64:67]
	v_mfma_f32_16x16x32_bf16 v[116:119], v[170:173], v[186:189], v[116:119]
	v_mfma_f32_16x16x32_bf16 v[112:115], v[178:181], v[186:189], v[112:115]
	v_mfma_f32_16x16x32_bf16 v[100:103], v[170:173], v[198:201], v[100:103]
	v_mfma_f32_16x16x32_bf16 v[96:99], v[178:181], v[198:201], v[96:99]
	v_mfma_f32_16x16x32_bf16 v[84:87], v[170:173], v[206:209], v[84:87]
	v_mfma_f32_16x16x32_bf16 v[80:83], v[178:181], v[206:209], v[80:83]
	v_mfma_f32_16x16x32_bf16 v[68:71], v[170:173], v[214:217], v[68:71]
	v_mfma_f32_16x16x32_bf16 v[64:67], v[178:181], v[214:217], v[64:67]
	s_setprio 0
	s_barrier
	s_add_i32 s48, s58, s3
	v_lshl_add_u64 v[194:195], s[28:29], 0, v[130:131]
	s_mov_b32 m0, s48
	ds_read_b128 v[182:185], v153 offset:16384
	ds_read_b128 v[186:189], v153 offset:17408
	ds_read_b128 v[190:193], v153 offset:18432
	ds_read_b128 v[198:201], v153 offset:19456
	ds_read_b128 v[202:205], v153 offset:20480
	ds_read_b128 v[206:209], v153 offset:21504
	ds_read_b128 v[210:213], v153 offset:22528
	ds_read_b128 v[214:217], v153 offset:23552
	global_load_lds_dwordx4 v[194:195], off
	s_add_i32 m0, s48, 0x2000
	s_add_u32 s48, s28, 0x40000
	v_lshl_add_u64 v[218:219], s[28:29], 0, v[134:135]
	s_addc_u32 s49, s29, 0
	s_add_i32 s64, s59, s3
	global_load_lds_dwordx4 v[218:219], off
	v_lshl_add_u64 v[220:221], s[48:49], 0, v[130:131]
	s_mov_b32 m0, s64
	v_lshl_add_u64 v[222:223], s[52:53], 0, v[132:133]
	global_load_lds_dwordx4 v[220:221], off
	v_lshl_add_u64 v[220:221], s[48:49], 0, v[134:135]
	s_add_i32 m0, s64, 0x2000
	s_nop 0
	global_load_lds_dwordx4 v[220:221], off
	v_lshl_add_u64 v[220:221], s[52:53], 0, v[128:129]
	s_mov_b32 m0, s14
	s_nop 0
	global_load_lds_dwordx4 v[220:221], off
	s_mov_b32 m0, s15
	s_nop 0
	global_load_lds_dwordx4 v[222:223], off
	s_waitcnt vmcnt(8)
	s_waitcnt lgkmcnt(0)
	s_barrier
	s_setprio 1
	v_mfma_f32_16x16x32_bf16 v[60:63], v[146:149], v[182:185], v[60:63]
	v_mfma_f32_16x16x32_bf16 v[56:59], v[158:161], v[182:185], v[56:59]
	v_mfma_f32_16x16x32_bf16 v[44:47], v[146:149], v[190:193], v[44:47]
	v_mfma_f32_16x16x32_bf16 v[40:43], v[158:161], v[190:193], v[40:43]
	v_mfma_f32_16x16x32_bf16 v[28:31], v[146:149], v[202:205], v[28:31]
	v_mfma_f32_16x16x32_bf16 v[24:27], v[158:161], v[202:205], v[24:27]
	v_mfma_f32_16x16x32_bf16 v[12:15], v[146:149], v[210:213], v[12:15]
	v_mfma_f32_16x16x32_bf16 v[8:11], v[158:161], v[210:213], v[8:11]
	v_mfma_f32_16x16x32_bf16 v[60:63], v[154:157], v[186:189], v[60:63]
	v_mfma_f32_16x16x32_bf16 v[56:59], v[162:165], v[186:189], v[56:59]
	v_mfma_f32_16x16x32_bf16 v[44:47], v[154:157], v[198:201], v[44:47]
	v_mfma_f32_16x16x32_bf16 v[40:43], v[162:165], v[198:201], v[40:43]
	v_mfma_f32_16x16x32_bf16 v[28:31], v[154:157], v[206:209], v[28:31]
	v_mfma_f32_16x16x32_bf16 v[24:27], v[162:165], v[206:209], v[24:27]
	v_mfma_f32_16x16x32_bf16 v[12:15], v[154:157], v[214:217], v[12:15]
	v_mfma_f32_16x16x32_bf16 v[8:11], v[162:165], v[214:217], v[8:11]
	v_mfma_f32_16x16x32_bf16 v[52:55], v[166:169], v[182:185], v[52:55]
	v_mfma_f32_16x16x32_bf16 v[48:51], v[174:177], v[182:185], v[48:51]
	v_mfma_f32_16x16x32_bf16 v[36:39], v[166:169], v[190:193], v[36:39]
	v_mfma_f32_16x16x32_bf16 v[32:35], v[174:177], v[190:193], v[32:35]
	v_mfma_f32_16x16x32_bf16 v[20:23], v[166:169], v[202:205], v[20:23]
	v_mfma_f32_16x16x32_bf16 v[16:19], v[174:177], v[202:205], v[16:19]
	v_mfma_f32_16x16x32_bf16 v[4:7], v[166:169], v[210:213], v[4:7]
	v_mfma_f32_16x16x32_bf16 v[0:3], v[174:177], v[210:213], v[0:3]
	v_mfma_f32_16x16x32_bf16 v[52:55], v[170:173], v[186:189], v[52:55]
	v_mfma_f32_16x16x32_bf16 v[48:51], v[178:181], v[186:189], v[48:51]
	v_mfma_f32_16x16x32_bf16 v[36:39], v[170:173], v[198:201], v[36:39]
	v_mfma_f32_16x16x32_bf16 v[32:35], v[178:181], v[198:201], v[32:35]
	v_mfma_f32_16x16x32_bf16 v[20:23], v[170:173], v[206:209], v[20:23]
	v_mfma_f32_16x16x32_bf16 v[16:19], v[178:181], v[206:209], v[16:19]
	v_mfma_f32_16x16x32_bf16 v[4:7], v[170:173], v[214:217], v[4:7]
	v_mfma_f32_16x16x32_bf16 v[0:3], v[178:181], v[214:217], v[0:3]
	s_setprio 0
	s_barrier
	s_add_i32 s64, 0, 0x18000
	s_add_i32 s65, 0, 0x1c000
	v_add_u32_e32 v162, s64, v150
	v_add_u32_e32 v178, s65, v150
	ds_read_b128 v[146:149], v162
	ds_read_b128 v[154:157], v162 offset:1024
	ds_read_b128 v[158:161], v162 offset:2048
	ds_read_b128 v[162:165], v162 offset:3072
	ds_read_b128 v[166:169], v178
	ds_read_b128 v[170:173], v178 offset:1024
	ds_read_b128 v[174:177], v178 offset:2048
	ds_read_b128 v[178:181], v178 offset:3072
	s_add_u32 s48, s52, 0x40000
	s_addc_u32 s49, s53, 0
	s_mov_b32 m0, s25
	v_lshl_add_u64 v[224:225], s[48:49], 0, v[128:129]
	ds_read_b128 v[182:185], v153 offset:32768
	ds_read_b128 v[186:189], v153 offset:33792
	ds_read_b128 v[190:193], v153 offset:34816
	ds_read_b128 v[198:201], v153 offset:35840
	ds_read_b128 v[202:205], v153 offset:36864
	ds_read_b128 v[206:209], v153 offset:37888
	ds_read_b128 v[210:213], v153 offset:38912
	ds_read_b128 v[214:217], v153 offset:39936
	global_load_lds_dwordx4 v[224:225], off
	v_lshl_add_u64 v[224:225], s[48:49], 0, v[132:133]
	s_mov_b32 m0, s46
	s_nop 0
	global_load_lds_dwordx4 v[224:225], off
	s_waitcnt vmcnt(8)
	s_waitcnt lgkmcnt(0)
	s_barrier
	s_setprio 1
	v_mfma_f32_16x16x32_bf16 v[124:127], v[146:149], v[182:185], v[124:127]
	v_mfma_f32_16x16x32_bf16 v[120:123], v[158:161], v[182:185], v[120:123]
	v_mfma_f32_16x16x32_bf16 v[108:111], v[146:149], v[190:193], v[108:111]
	v_mfma_f32_16x16x32_bf16 v[104:107], v[158:161], v[190:193], v[104:107]
	v_mfma_f32_16x16x32_bf16 v[92:95], v[146:149], v[202:205], v[92:95]
	v_mfma_f32_16x16x32_bf16 v[88:91], v[158:161], v[202:205], v[88:91]
	v_mfma_f32_16x16x32_bf16 v[76:79], v[146:149], v[210:213], v[76:79]
	v_mfma_f32_16x16x32_bf16 v[72:75], v[158:161], v[210:213], v[72:75]
	v_mfma_f32_16x16x32_bf16 v[124:127], v[154:157], v[186:189], v[124:127]
	v_mfma_f32_16x16x32_bf16 v[120:123], v[162:165], v[186:189], v[120:123]
	v_mfma_f32_16x16x32_bf16 v[108:111], v[154:157], v[198:201], v[108:111]
	v_mfma_f32_16x16x32_bf16 v[104:107], v[162:165], v[198:201], v[104:107]
	v_mfma_f32_16x16x32_bf16 v[92:95], v[154:157], v[206:209], v[92:95]
	v_mfma_f32_16x16x32_bf16 v[88:91], v[162:165], v[206:209], v[88:91]
	v_mfma_f32_16x16x32_bf16 v[76:79], v[154:157], v[214:217], v[76:79]
	v_mfma_f32_16x16x32_bf16 v[72:75], v[162:165], v[214:217], v[72:75]
	v_mfma_f32_16x16x32_bf16 v[116:119], v[166:169], v[182:185], v[116:119]
	v_mfma_f32_16x16x32_bf16 v[112:115], v[174:177], v[182:185], v[112:115]
	v_mfma_f32_16x16x32_bf16 v[100:103], v[166:169], v[190:193], v[100:103]
	v_mfma_f32_16x16x32_bf16 v[96:99], v[174:177], v[190:193], v[96:99]
	v_mfma_f32_16x16x32_bf16 v[84:87], v[166:169], v[202:205], v[84:87]
	v_mfma_f32_16x16x32_bf16 v[80:83], v[174:177], v[202:205], v[80:83]
	v_mfma_f32_16x16x32_bf16 v[68:71], v[166:169], v[210:213], v[68:71]
	v_mfma_f32_16x16x32_bf16 v[64:67], v[174:177], v[210:213], v[64:67]
	v_mfma_f32_16x16x32_bf16 v[116:119], v[170:173], v[186:189], v[116:119]
	v_mfma_f32_16x16x32_bf16 v[112:115], v[178:181], v[186:189], v[112:115]
	v_mfma_f32_16x16x32_bf16 v[100:103], v[170:173], v[198:201], v[100:103]
	v_mfma_f32_16x16x32_bf16 v[96:99], v[178:181], v[198:201], v[96:99]
	v_mfma_f32_16x16x32_bf16 v[84:87], v[170:173], v[206:209], v[84:87]
	v_mfma_f32_16x16x32_bf16 v[80:83], v[178:181], v[206:209], v[80:83]
	v_mfma_f32_16x16x32_bf16 v[68:71], v[170:173], v[214:217], v[68:71]
	v_mfma_f32_16x16x32_bf16 v[64:67], v[178:181], v[214:217], v[64:67]
	s_setprio 0
	s_barrier
	s_add_i32 s48, s64, s3
	v_lshl_add_u64 v[194:195], v[194:195], 0, s[8:9]
	s_mov_b32 m0, s48
	ds_read_b128 v[182:185], v153 offset:49152
	ds_read_b128 v[186:189], v153 offset:50176
	ds_read_b128 v[190:193], v153 offset:51200
	ds_read_b128 v[198:201], v153 offset:52224
	ds_read_b128 v[202:205], v153 offset:53248
	ds_read_b128 v[206:209], v153 offset:54272
	ds_read_b128 v[210:213], v153 offset:55296
	ds_read_b128 v[214:217], v153 offset:56320
	global_load_lds_dwordx4 v[194:195], off
	s_add_i32 m0, s48, 0x2000
	s_add_u32 s28, s28, 0x40080
	v_lshl_add_u64 v[194:195], v[218:219], 0, s[8:9]
	s_addc_u32 s29, s29, 0
	s_add_i32 s48, s65, s3
	global_load_lds_dwordx4 v[194:195], off
	v_lshl_add_u64 v[194:195], s[28:29], 0, v[130:131]
	s_mov_b32 m0, s48
	s_nop 0
	global_load_lds_dwordx4 v[194:195], off
	v_lshl_add_u64 v[194:195], s[28:29], 0, v[134:135]
	s_add_i32 m0, s48, 0x2000
	s_nop 0
	global_load_lds_dwordx4 v[194:195], off
	v_lshl_add_u64 v[194:195], v[220:221], 0, s[8:9]
	s_mov_b32 m0, s54
	s_nop 0
	global_load_lds_dwordx4 v[194:195], off
	v_lshl_add_u64 v[194:195], v[222:223], 0, s[8:9]
	s_mov_b32 m0, s55
	s_nop 0
	global_load_lds_dwordx4 v[194:195], off
	s_waitcnt vmcnt(8)
	s_waitcnt lgkmcnt(0)
	s_barrier
	s_setprio 1
	v_mfma_f32_16x16x32_bf16 v[60:63], v[146:149], v[182:185], v[60:63]
	v_mfma_f32_16x16x32_bf16 v[56:59], v[158:161], v[182:185], v[56:59]
	v_mfma_f32_16x16x32_bf16 v[44:47], v[146:149], v[190:193], v[44:47]
	v_mfma_f32_16x16x32_bf16 v[40:43], v[158:161], v[190:193], v[40:43]
	v_mfma_f32_16x16x32_bf16 v[28:31], v[146:149], v[202:205], v[28:31]
	v_mfma_f32_16x16x32_bf16 v[24:27], v[158:161], v[202:205], v[24:27]
	v_mfma_f32_16x16x32_bf16 v[12:15], v[146:149], v[210:213], v[12:15]
	v_mfma_f32_16x16x32_bf16 v[8:11], v[158:161], v[210:213], v[8:11]
	v_mfma_f32_16x16x32_bf16 v[60:63], v[154:157], v[186:189], v[60:63]
	v_mfma_f32_16x16x32_bf16 v[56:59], v[162:165], v[186:189], v[56:59]
	v_mfma_f32_16x16x32_bf16 v[44:47], v[154:157], v[198:201], v[44:47]
	v_mfma_f32_16x16x32_bf16 v[40:43], v[162:165], v[198:201], v[40:43]
	v_mfma_f32_16x16x32_bf16 v[28:31], v[154:157], v[206:209], v[28:31]
	v_mfma_f32_16x16x32_bf16 v[24:27], v[162:165], v[206:209], v[24:27]
	v_mfma_f32_16x16x32_bf16 v[12:15], v[154:157], v[214:217], v[12:15]
	v_mfma_f32_16x16x32_bf16 v[8:11], v[162:165], v[214:217], v[8:11]
	v_mfma_f32_16x16x32_bf16 v[52:55], v[166:169], v[182:185], v[52:55]
	v_mfma_f32_16x16x32_bf16 v[48:51], v[174:177], v[182:185], v[48:51]
	v_mfma_f32_16x16x32_bf16 v[36:39], v[166:169], v[190:193], v[36:39]
	v_mfma_f32_16x16x32_bf16 v[32:35], v[174:177], v[190:193], v[32:35]
	v_mfma_f32_16x16x32_bf16 v[20:23], v[166:169], v[202:205], v[20:23]
	v_mfma_f32_16x16x32_bf16 v[16:19], v[174:177], v[202:205], v[16:19]
	v_mfma_f32_16x16x32_bf16 v[4:7], v[166:169], v[210:213], v[4:7]
	v_mfma_f32_16x16x32_bf16 v[0:3], v[174:177], v[210:213], v[0:3]
	v_mfma_f32_16x16x32_bf16 v[52:55], v[170:173], v[186:189], v[52:55]
	v_mfma_f32_16x16x32_bf16 v[48:51], v[178:181], v[186:189], v[48:51]
	v_mfma_f32_16x16x32_bf16 v[36:39], v[170:173], v[198:201], v[36:39]
	v_mfma_f32_16x16x32_bf16 v[32:35], v[178:181], v[198:201], v[32:35]
	v_mfma_f32_16x16x32_bf16 v[20:23], v[170:173], v[206:209], v[20:23]
	v_mfma_f32_16x16x32_bf16 v[16:19], v[178:181], v[206:209], v[16:19]
	v_mfma_f32_16x16x32_bf16 v[4:7], v[170:173], v[214:217], v[4:7]
	v_mfma_f32_16x16x32_bf16 v[0:3], v[178:181], v[214:217], v[0:3]
	s_setprio 0
	s_barrier
	s_add_i32 s63, s63, 2
	s_add_u32 s26, s26, 0x100
	s_addc_u32 s27, s27, 0
	s_add_u32 s61, s61, 0x100
	s_addc_u32 s62, s62, 0
	s_cmp_gt_u32 s63, 13
	s_cbranch_scc0 .LBB0_966
	s_and_b64 vcc, exec, s[10:11]
	s_cbranch_vccz .LBB0_969
	s_barrier

.LBB0_1037:
	ds_read_b128 v[144:147], v165
	ds_read_b128 v[148:151], v165 offset:1024
	ds_read_b128 v[152:155], v165 offset:2048
	ds_read_b128 v[156:159], v165 offset:3072
	ds_read_b128 v[170:173], v166
	ds_read_b128 v[174:177], v166 offset:1024
	ds_read_b128 v[178:181], v166 offset:2048
	ds_read_b128 v[182:185], v166 offset:3072
	s_add_u32 s62, s60, 0xfffc0080
	s_addc_u32 s63, s61, -1
	s_cmp_eq_u32 s77, 12
	s_cselect_b32 s65, s12, s63
	s_cselect_b32 s64, s13, s62
	s_cselect_b32 s63, s45, s76
	s_cselect_b32 s62, s49, s75
	v_lshl_add_u64 v[160:161], s[60:61], 0, v[136:137]
	s_add_i32 m0, s3, 0xc000
	ds_read_b128 v[186:189], v167
	ds_read_b128 v[190:193], v167 offset:1024
	ds_read_b128 v[198:201], v167 offset:2048
	ds_read_b128 v[202:205], v167 offset:3072
	ds_read_b128 v[206:209], v167 offset:4096
	ds_read_b128 v[210:213], v167 offset:5120
	ds_read_b128 v[214:217], v167 offset:6144
	ds_read_b128 v[218:221], v167 offset:7168
	global_load_lds_dwordx4 v[160:161], off
	v_lshl_add_u64 v[160:161], s[60:61], 0, v[138:139]
	s_add_i32 m0, s3, 0xe000
	s_nop 0
	global_load_lds_dwordx4 v[160:161], off
	s_waitcnt vmcnt(8)
	s_waitcnt lgkmcnt(0)
	s_barrier
	s_setprio 1
	v_mfma_f32_16x16x32_bf16 v[124:127], v[144:147], v[186:189], v[124:127]
	v_mfma_f32_16x16x32_bf16 v[120:123], v[152:155], v[186:189], v[120:123]
	v_mfma_f32_16x16x32_bf16 v[108:111], v[144:147], v[198:201], v[108:111]
	v_mfma_f32_16x16x32_bf16 v[104:107], v[152:155], v[198:201], v[104:107]
	v_mfma_f32_16x16x32_bf16 v[92:95], v[144:147], v[206:209], v[92:95]
	v_mfma_f32_16x16x32_bf16 v[88:91], v[152:155], v[206:209], v[88:91]
	v_mfma_f32_16x16x32_bf16 v[76:79], v[144:147], v[214:217], v[76:79]
	v_mfma_f32_16x16x32_bf16 v[72:75], v[152:155], v[214:217], v[72:75]
	v_mfma_f32_16x16x32_bf16 v[124:127], v[148:151], v[190:193], v[124:127]
	v_mfma_f32_16x16x32_bf16 v[120:123], v[156:159], v[190:193], v[120:123]
	v_mfma_f32_16x16x32_bf16 v[108:111], v[148:151], v[202:205], v[108:111]
	v_mfma_f32_16x16x32_bf16 v[104:107], v[156:159], v[202:205], v[104:107]
	v_mfma_f32_16x16x32_bf16 v[92:95], v[148:151], v[210:213], v[92:95]
	v_mfma_f32_16x16x32_bf16 v[88:91], v[156:159], v[210:213], v[88:91]
	v_mfma_f32_16x16x32_bf16 v[76:79], v[148:151], v[218:221], v[76:79]
	v_mfma_f32_16x16x32_bf16 v[72:75], v[156:159], v[218:221], v[72:75]
	v_mfma_f32_16x16x32_bf16 v[116:119], v[170:173], v[186:189], v[116:119]
	v_mfma_f32_16x16x32_bf16 v[112:115], v[178:181], v[186:189], v[112:115]
	v_mfma_f32_16x16x32_bf16 v[100:103], v[170:173], v[198:201], v[100:103]
	v_mfma_f32_16x16x32_bf16 v[96:99], v[178:181], v[198:201], v[96:99]
	v_mfma_f32_16x16x32_bf16 v[84:87], v[170:173], v[206:209], v[84:87]
	v_mfma_f32_16x16x32_bf16 v[80:83], v[178:181], v[206:209], v[80:83]
	v_mfma_f32_16x16x32_bf16 v[68:71], v[170:173], v[214:217], v[68:71]
	v_mfma_f32_16x16x32_bf16 v[64:67], v[178:181], v[214:217], v[64:67]
	v_mfma_f32_16x16x32_bf16 v[116:119], v[174:177], v[190:193], v[116:119]
	v_mfma_f32_16x16x32_bf16 v[112:115], v[182:185], v[190:193], v[112:115]
	v_mfma_f32_16x16x32_bf16 v[100:103], v[174:177], v[202:205], v[100:103]
	v_mfma_f32_16x16x32_bf16 v[96:99], v[182:185], v[202:205], v[96:99]
	v_mfma_f32_16x16x32_bf16 v[84:87], v[174:177], v[210:213], v[84:87]
	v_mfma_f32_16x16x32_bf16 v[80:83], v[182:185], v[210:213], v[80:83]
	v_mfma_f32_16x16x32_bf16 v[68:71], v[174:177], v[218:221], v[68:71]
	v_mfma_f32_16x16x32_bf16 v[64:67], v[182:185], v[218:221], v[64:67]
	s_setprio 0
	s_barrier
	s_add_i32 s78, s73, s2
	v_lshl_add_u64 v[160:161], s[62:63], 0, v[130:131]
	s_mov_b32 m0, s78
	ds_read_b128 v[186:189], v167 offset:16384
	ds_read_b128 v[190:193], v167 offset:17408
	ds_read_b128 v[198:201], v167 offset:18432
	ds_read_b128 v[202:205], v167 offset:19456
	ds_read_b128 v[206:209], v167 offset:20480
	ds_read_b128 v[210:213], v167 offset:21504
	ds_read_b128 v[214:217], v167 offset:22528
	ds_read_b128 v[218:221], v167 offset:23552
	global_load_lds_dwordx4 v[160:161], off
	s_add_i32 m0, s78, 0x2000
	s_add_u32 s78, s62, 0x40000
	v_lshl_add_u64 v[194:195], s[62:63], 0, v[134:135]
	s_addc_u32 s79, s63, 0
	s_add_i32 s80, s74, s2
	global_load_lds_dwordx4 v[194:195], off
	v_lshl_add_u64 v[222:223], s[78:79], 0, v[130:131]
	s_mov_b32 m0, s80
	v_lshl_add_u64 v[224:225], s[64:65], 0, v[132:133]
	global_load_lds_dwordx4 v[222:223], off
	v_lshl_add_u64 v[222:223], s[78:79], 0, v[134:135]
	s_add_i32 m0, s80, 0x2000
	s_nop 0
	global_load_lds_dwordx4 v[222:223], off
	v_lshl_add_u64 v[222:223], s[64:65], 0, v[128:129]
	s_mov_b32 m0, s3
	s_nop 0
	global_load_lds_dwordx4 v[222:223], off
	s_mov_b32 m0, s14
	s_nop 0
	global_load_lds_dwordx4 v[224:225], off
	s_waitcnt vmcnt(8)
	s_waitcnt lgkmcnt(0)
	s_barrier
	s_setprio 1
	v_mfma_f32_16x16x32_bf16 v[60:63], v[144:147], v[186:189], v[60:63]
	v_mfma_f32_16x16x32_bf16 v[56:59], v[152:155], v[186:189], v[56:59]
	v_mfma_f32_16x16x32_bf16 v[44:47], v[144:147], v[198:201], v[44:47]
	v_mfma_f32_16x16x32_bf16 v[40:43], v[152:155], v[198:201], v[40:43]
	v_mfma_f32_16x16x32_bf16 v[28:31], v[144:147], v[206:209], v[28:31]
	v_mfma_f32_16x16x32_bf16 v[24:27], v[152:155], v[206:209], v[24:27]
	v_mfma_f32_16x16x32_bf16 v[12:15], v[144:147], v[214:217], v[12:15]
	v_mfma_f32_16x16x32_bf16 v[8:11], v[152:155], v[214:217], v[8:11]
	v_mfma_f32_16x16x32_bf16 v[60:63], v[148:151], v[190:193], v[60:63]
	v_mfma_f32_16x16x32_bf16 v[56:59], v[156:159], v[190:193], v[56:59]
	v_mfma_f32_16x16x32_bf16 v[44:47], v[148:151], v[202:205], v[44:47]
	v_mfma_f32_16x16x32_bf16 v[40:43], v[156:159], v[202:205], v[40:43]
	v_mfma_f32_16x16x32_bf16 v[28:31], v[148:151], v[210:213], v[28:31]
	v_mfma_f32_16x16x32_bf16 v[24:27], v[156:159], v[210:213], v[24:27]
	v_mfma_f32_16x16x32_bf16 v[12:15], v[148:151], v[218:221], v[12:15]
	v_mfma_f32_16x16x32_bf16 v[8:11], v[156:159], v[218:221], v[8:11]
	v_mfma_f32_16x16x32_bf16 v[52:55], v[170:173], v[186:189], v[52:55]
	v_mfma_f32_16x16x32_bf16 v[48:51], v[178:181], v[186:189], v[48:51]
	v_mfma_f32_16x16x32_bf16 v[36:39], v[170:173], v[198:201], v[36:39]
	v_mfma_f32_16x16x32_bf16 v[32:35], v[178:181], v[198:201], v[32:35]
	v_mfma_f32_16x16x32_bf16 v[20:23], v[170:173], v[206:209], v[20:23]
	v_mfma_f32_16x16x32_bf16 v[16:19], v[178:181], v[206:209], v[16:19]
	v_mfma_f32_16x16x32_bf16 v[4:7], v[170:173], v[214:217], v[4:7]
	v_mfma_f32_16x16x32_bf16 v[0:3], v[178:181], v[214:217], v[0:3]
	v_mfma_f32_16x16x32_bf16 v[52:55], v[174:177], v[190:193], v[52:55]
	v_mfma_f32_16x16x32_bf16 v[48:51], v[182:185], v[190:193], v[48:51]
	v_mfma_f32_16x16x32_bf16 v[36:39], v[174:177], v[202:205], v[36:39]
	v_mfma_f32_16x16x32_bf16 v[32:35], v[182:185], v[202:205], v[32:35]
	v_mfma_f32_16x16x32_bf16 v[20:23], v[174:177], v[210:213], v[20:23]
	v_mfma_f32_16x16x32_bf16 v[16:19], v[182:185], v[210:213], v[16:19]
	v_mfma_f32_16x16x32_bf16 v[4:7], v[174:177], v[218:221], v[4:7]
	v_mfma_f32_16x16x32_bf16 v[0:3], v[182:185], v[218:221], v[0:3]
	s_setprio 0
	s_barrier
	s_add_i32 s78, 0, 0x18000
	s_add_i32 s79, 0, 0x1c000
	v_add_u32_e32 v156, s78, v163
	v_add_u32_e32 v169, s79, v163
	ds_read_b128 v[144:147], v156
	ds_read_b128 v[148:151], v156 offset:1024
	ds_read_b128 v[152:155], v156 offset:2048
	ds_read_b128 v[156:159], v156 offset:3072
	ds_read_b128 v[170:173], v169
	ds_read_b128 v[174:177], v169 offset:1024
	ds_read_b128 v[178:181], v169 offset:2048
	ds_read_b128 v[182:185], v169 offset:3072
	s_add_u32 s64, s64, 0x40000
	s_addc_u32 s65, s65, 0
	s_mov_b32 m0, s15
	v_lshl_add_u64 v[226:227], s[64:65], 0, v[128:129]
	ds_read_b128 v[186:189], v167 offset:32768
	ds_read_b128 v[190:193], v167 offset:33792
	ds_read_b128 v[198:201], v167 offset:34816
	ds_read_b128 v[202:205], v167 offset:35840
	ds_read_b128 v[206:209], v167 offset:36864
	ds_read_b128 v[210:213], v167 offset:37888
	ds_read_b128 v[214:217], v167 offset:38912
	ds_read_b128 v[218:221], v167 offset:39936
	global_load_lds_dwordx4 v[226:227], off
	v_lshl_add_u64 v[226:227], s[64:65], 0, v[132:133]
	s_mov_b32 m0, s46
	s_nop 0
	global_load_lds_dwordx4 v[226:227], off
	s_waitcnt vmcnt(8)
	s_waitcnt lgkmcnt(0)
	s_barrier
	s_setprio 1
	v_mfma_f32_16x16x32_bf16 v[124:127], v[144:147], v[186:189], v[124:127]
	v_mfma_f32_16x16x32_bf16 v[120:123], v[152:155], v[186:189], v[120:123]
	v_mfma_f32_16x16x32_bf16 v[108:111], v[144:147], v[198:201], v[108:111]
	v_mfma_f32_16x16x32_bf16 v[104:107], v[152:155], v[198:201], v[104:107]
	v_mfma_f32_16x16x32_bf16 v[92:95], v[144:147], v[206:209], v[92:95]
	v_mfma_f32_16x16x32_bf16 v[88:91], v[152:155], v[206:209], v[88:91]
	v_mfma_f32_16x16x32_bf16 v[76:79], v[144:147], v[214:217], v[76:79]
	v_mfma_f32_16x16x32_bf16 v[72:75], v[152:155], v[214:217], v[72:75]
	v_mfma_f32_16x16x32_bf16 v[124:127], v[148:151], v[190:193], v[124:127]
	v_mfma_f32_16x16x32_bf16 v[120:123], v[156:159], v[190:193], v[120:123]
	v_mfma_f32_16x16x32_bf16 v[108:111], v[148:151], v[202:205], v[108:111]
	v_mfma_f32_16x16x32_bf16 v[104:107], v[156:159], v[202:205], v[104:107]
	v_mfma_f32_16x16x32_bf16 v[92:95], v[148:151], v[210:213], v[92:95]
	v_mfma_f32_16x16x32_bf16 v[88:91], v[156:159], v[210:213], v[88:91]
	v_mfma_f32_16x16x32_bf16 v[76:79], v[148:151], v[218:221], v[76:79]
	v_mfma_f32_16x16x32_bf16 v[72:75], v[156:159], v[218:221], v[72:75]
	v_mfma_f32_16x16x32_bf16 v[116:119], v[170:173], v[186:189], v[116:119]
	v_mfma_f32_16x16x32_bf16 v[112:115], v[178:181], v[186:189], v[112:115]
	v_mfma_f32_16x16x32_bf16 v[100:103], v[170:173], v[198:201], v[100:103]
	v_mfma_f32_16x16x32_bf16 v[96:99], v[178:181], v[198:201], v[96:99]
	v_mfma_f32_16x16x32_bf16 v[84:87], v[170:173], v[206:209], v[84:87]
	v_mfma_f32_16x16x32_bf16 v[80:83], v[178:181], v[206:209], v[80:83]
	v_mfma_f32_16x16x32_bf16 v[68:71], v[170:173], v[214:217], v[68:71]
	v_mfma_f32_16x16x32_bf16 v[64:67], v[178:181], v[214:217], v[64:67]
	v_mfma_f32_16x16x32_bf16 v[116:119], v[174:177], v[190:193], v[116:119]
	v_mfma_f32_16x16x32_bf16 v[112:115], v[182:185], v[190:193], v[112:115]
	v_mfma_f32_16x16x32_bf16 v[100:103], v[174:177], v[202:205], v[100:103]
	v_mfma_f32_16x16x32_bf16 v[96:99], v[182:185], v[202:205], v[96:99]
	v_mfma_f32_16x16x32_bf16 v[84:87], v[174:177], v[210:213], v[84:87]
	v_mfma_f32_16x16x32_bf16 v[80:83], v[182:185], v[210:213], v[80:83]
	v_mfma_f32_16x16x32_bf16 v[68:71], v[174:177], v[218:221], v[68:71]
	v_mfma_f32_16x16x32_bf16 v[64:67], v[182:185], v[218:221], v[64:67]
	s_setprio 0
	s_barrier
	s_add_i32 s64, s78, s2
	v_lshl_add_u64 v[160:161], v[160:161], 0, s[18:19]
	s_mov_b32 m0, s64
	ds_read_b128 v[186:189], v167 offset:49152
	ds_read_b128 v[190:193], v167 offset:50176
	ds_read_b128 v[198:201], v167 offset:51200
	ds_read_b128 v[202:205], v167 offset:52224
	ds_read_b128 v[206:209], v167 offset:53248
	ds_read_b128 v[210:213], v167 offset:54272
	ds_read_b128 v[214:217], v167 offset:55296
	ds_read_b128 v[218:221], v167 offset:56320
	global_load_lds_dwordx4 v[160:161], off
	s_add_i32 m0, s64, 0x2000
	s_add_u32 s62, s62, 0x40080
	v_lshl_add_u64 v[160:161], v[194:195], 0, s[18:19]
	s_addc_u32 s63, s63, 0
	s_add_i32 s64, s79, s2
	global_load_lds_dwordx4 v[160:161], off
	v_lshl_add_u64 v[160:161], s[62:63], 0, v[130:131]
	s_mov_b32 m0, s64
	s_nop 0
	global_load_lds_dwordx4 v[160:161], off
	v_lshl_add_u64 v[160:161], s[62:63], 0, v[134:135]
	s_add_i32 m0, s64, 0x2000
	s_nop 0
	global_load_lds_dwordx4 v[160:161], off
	v_lshl_add_u64 v[160:161], v[222:223], 0, s[18:19]
	s_mov_b32 m0, s66
	s_nop 0
	global_load_lds_dwordx4 v[160:161], off
	v_lshl_add_u64 v[160:161], v[224:225], 0, s[18:19]
	s_mov_b32 m0, s67
	s_nop 0
	global_load_lds_dwordx4 v[160:161], off
	s_waitcnt vmcnt(8)
	s_waitcnt lgkmcnt(0)
	s_barrier
	s_setprio 1
	v_mfma_f32_16x16x32_bf16 v[60:63], v[144:147], v[186:189], v[60:63]
	v_mfma_f32_16x16x32_bf16 v[56:59], v[152:155], v[186:189], v[56:59]
	v_mfma_f32_16x16x32_bf16 v[44:47], v[144:147], v[198:201], v[44:47]
	v_mfma_f32_16x16x32_bf16 v[40:43], v[152:155], v[198:201], v[40:43]
	v_mfma_f32_16x16x32_bf16 v[28:31], v[144:147], v[206:209], v[28:31]
	v_mfma_f32_16x16x32_bf16 v[24:27], v[152:155], v[206:209], v[24:27]
	v_mfma_f32_16x16x32_bf16 v[12:15], v[144:147], v[214:217], v[12:15]
	v_mfma_f32_16x16x32_bf16 v[8:11], v[152:155], v[214:217], v[8:11]
	v_mfma_f32_16x16x32_bf16 v[60:63], v[148:151], v[190:193], v[60:63]
	v_mfma_f32_16x16x32_bf16 v[56:59], v[156:159], v[190:193], v[56:59]
	v_mfma_f32_16x16x32_bf16 v[44:47], v[148:151], v[202:205], v[44:47]
	v_mfma_f32_16x16x32_bf16 v[40:43], v[156:159], v[202:205], v[40:43]
	v_mfma_f32_16x16x32_bf16 v[28:31], v[148:151], v[210:213], v[28:31]
	v_mfma_f32_16x16x32_bf16 v[24:27], v[156:159], v[210:213], v[24:27]
	v_mfma_f32_16x16x32_bf16 v[12:15], v[148:151], v[218:221], v[12:15]
	v_mfma_f32_16x16x32_bf16 v[8:11], v[156:159], v[218:221], v[8:11]
	v_mfma_f32_16x16x32_bf16 v[52:55], v[170:173], v[186:189], v[52:55]
	v_mfma_f32_16x16x32_bf16 v[48:51], v[178:181], v[186:189], v[48:51]
	v_mfma_f32_16x16x32_bf16 v[36:39], v[170:173], v[198:201], v[36:39]
	v_mfma_f32_16x16x32_bf16 v[32:35], v[178:181], v[198:201], v[32:35]
	v_mfma_f32_16x16x32_bf16 v[20:23], v[170:173], v[206:209], v[20:23]
	v_mfma_f32_16x16x32_bf16 v[16:19], v[178:181], v[206:209], v[16:19]
	v_mfma_f32_16x16x32_bf16 v[4:7], v[170:173], v[214:217], v[4:7]
	v_mfma_f32_16x16x32_bf16 v[0:3], v[178:181], v[214:217], v[0:3]
	v_mfma_f32_16x16x32_bf16 v[52:55], v[174:177], v[190:193], v[52:55]
	v_mfma_f32_16x16x32_bf16 v[48:51], v[182:185], v[190:193], v[48:51]
	v_mfma_f32_16x16x32_bf16 v[36:39], v[174:177], v[202:205], v[36:39]
	v_mfma_f32_16x16x32_bf16 v[32:35], v[182:185], v[202:205], v[32:35]
	v_mfma_f32_16x16x32_bf16 v[20:23], v[174:177], v[210:213], v[20:23]
	v_mfma_f32_16x16x32_bf16 v[16:19], v[182:185], v[210:213], v[16:19]
	v_mfma_f32_16x16x32_bf16 v[4:7], v[174:177], v[218:221], v[4:7]
	v_mfma_f32_16x16x32_bf16 v[0:3], v[182:185], v[218:221], v[0:3]
	s_setprio 0
	s_barrier
	s_add_i32 s77, s77, 2
	s_add_u32 s60, s60, 0x100
	s_addc_u32 s61, s61, 0
	s_add_u32 s75, s75, 0x100
	s_addc_u32 s76, s76, 0
	s_cmp_gt_u32 s77, 13
	s_cbranch_scc0 .LBB0_1037
	s_and_b64 vcc, exec, s[20:21]
	s_cbranch_vccz .LBB0_1040
	s_barrier

.LBB0_1122:
	ds_read_b128 v[156:159], v151
	ds_read_b128 v[160:163], v151 offset:1024
	ds_read_b128 v[164:167], v151 offset:2048
	ds_read_b128 v[168:171], v151 offset:3072
	ds_read_b128 v[172:175], v152
	ds_read_b128 v[176:179], v152 offset:1024
	ds_read_b128 v[180:183], v152 offset:2048
	ds_read_b128 v[184:187], v152 offset:3072
	s_add_u32 s40, s36, 0xfffc0080
	s_addc_u32 s41, s37, -1
	s_cmp_eq_u32 s63, 12
	s_cselect_b32 s45, s12, s41
	s_cselect_b32 s44, s13, s40
	s_cselect_b32 s41, s21, s62
	s_cselect_b32 s40, s23, s61
	v_lshl_add_u64 v[148:149], s[36:37], 0, v[140:141]
	s_add_i32 m0, s15, 0xc000
	ds_read_b128 v[188:191], v153
	ds_read_b128 v[192:195], v153 offset:1024
	ds_read_b128 v[198:201], v153 offset:2048
	ds_read_b128 v[202:205], v153 offset:3072
	ds_read_b128 v[206:209], v153 offset:4096
	ds_read_b128 v[210:213], v153 offset:5120
	ds_read_b128 v[214:217], v153 offset:6144
	ds_read_b128 v[218:221], v153 offset:7168
	global_load_lds_dwordx4 v[148:149], off
	v_lshl_add_u64 v[148:149], s[36:37], 0, v[142:143]
	s_add_i32 m0, s15, 0xe000
	s_nop 0
	global_load_lds_dwordx4 v[148:149], off
	s_waitcnt vmcnt(8)
	s_waitcnt lgkmcnt(0)
	s_barrier
	s_setprio 1
	v_mfma_f32_16x16x32_bf16 v[124:127], v[156:159], v[188:191], v[124:127]
	v_mfma_f32_16x16x32_bf16 v[120:123], v[164:167], v[188:191], v[120:123]
	v_mfma_f32_16x16x32_bf16 v[108:111], v[156:159], v[198:201], v[108:111]
	v_mfma_f32_16x16x32_bf16 v[104:107], v[164:167], v[198:201], v[104:107]
	v_mfma_f32_16x16x32_bf16 v[92:95], v[156:159], v[206:209], v[92:95]
	v_mfma_f32_16x16x32_bf16 v[88:91], v[164:167], v[206:209], v[88:91]
	v_mfma_f32_16x16x32_bf16 v[76:79], v[156:159], v[214:217], v[76:79]
	v_mfma_f32_16x16x32_bf16 v[72:75], v[164:167], v[214:217], v[72:75]
	v_mfma_f32_16x16x32_bf16 v[124:127], v[160:163], v[192:195], v[124:127]
	v_mfma_f32_16x16x32_bf16 v[120:123], v[168:171], v[192:195], v[120:123]
	v_mfma_f32_16x16x32_bf16 v[108:111], v[160:163], v[202:205], v[108:111]
	v_mfma_f32_16x16x32_bf16 v[104:107], v[168:171], v[202:205], v[104:107]
	v_mfma_f32_16x16x32_bf16 v[92:95], v[160:163], v[210:213], v[92:95]
	v_mfma_f32_16x16x32_bf16 v[88:91], v[168:171], v[210:213], v[88:91]
	v_mfma_f32_16x16x32_bf16 v[76:79], v[160:163], v[218:221], v[76:79]
	v_mfma_f32_16x16x32_bf16 v[72:75], v[168:171], v[218:221], v[72:75]
	v_mfma_f32_16x16x32_bf16 v[116:119], v[172:175], v[188:191], v[116:119]
	v_mfma_f32_16x16x32_bf16 v[112:115], v[180:183], v[188:191], v[112:115]
	v_mfma_f32_16x16x32_bf16 v[100:103], v[172:175], v[198:201], v[100:103]
	v_mfma_f32_16x16x32_bf16 v[96:99], v[180:183], v[198:201], v[96:99]
	v_mfma_f32_16x16x32_bf16 v[84:87], v[172:175], v[206:209], v[84:87]
	v_mfma_f32_16x16x32_bf16 v[80:83], v[180:183], v[206:209], v[80:83]
	v_mfma_f32_16x16x32_bf16 v[68:71], v[172:175], v[214:217], v[68:71]
	v_mfma_f32_16x16x32_bf16 v[64:67], v[180:183], v[214:217], v[64:67]
	v_mfma_f32_16x16x32_bf16 v[116:119], v[176:179], v[192:195], v[116:119]
	v_mfma_f32_16x16x32_bf16 v[112:115], v[184:187], v[192:195], v[112:115]
	v_mfma_f32_16x16x32_bf16 v[100:103], v[176:179], v[202:205], v[100:103]
	v_mfma_f32_16x16x32_bf16 v[96:99], v[184:187], v[202:205], v[96:99]
	v_mfma_f32_16x16x32_bf16 v[84:87], v[176:179], v[210:213], v[84:87]
	v_mfma_f32_16x16x32_bf16 v[80:83], v[184:187], v[210:213], v[80:83]
	v_mfma_f32_16x16x32_bf16 v[68:71], v[176:179], v[218:221], v[68:71]
	v_mfma_f32_16x16x32_bf16 v[64:67], v[184:187], v[218:221], v[64:67]
	s_setprio 0
	s_barrier
	s_add_i32 s64, s57, s2
	v_lshl_add_u64 v[148:149], s[40:41], 0, v[132:133]
	s_mov_b32 m0, s64
	ds_read_b128 v[188:191], v153 offset:16384
	ds_read_b128 v[192:195], v153 offset:17408
	ds_read_b128 v[198:201], v153 offset:18432
	ds_read_b128 v[202:205], v153 offset:19456
	ds_read_b128 v[206:209], v153 offset:20480
	ds_read_b128 v[210:213], v153 offset:21504
	ds_read_b128 v[214:217], v153 offset:22528
	ds_read_b128 v[218:221], v153 offset:23552
	global_load_lds_dwordx4 v[148:149], off
	s_add_i32 m0, s64, 0x2000
	s_add_u32 s64, s40, 0x40000
	v_lshl_add_u64 v[222:223], s[40:41], 0, v[128:129]
	s_addc_u32 s65, s41, 0
	s_add_i32 s66, s58, s2
	global_load_lds_dwordx4 v[222:223], off
	v_lshl_add_u64 v[224:225], s[64:65], 0, v[132:133]
	s_mov_b32 m0, s66
	v_lshl_add_u64 v[226:227], s[44:45], 0, v[130:131]
	global_load_lds_dwordx4 v[224:225], off
	v_lshl_add_u64 v[224:225], s[64:65], 0, v[128:129]
	s_add_i32 m0, s66, 0x2000
	s_nop 0
	global_load_lds_dwordx4 v[224:225], off
	v_lshl_add_u64 v[224:225], s[44:45], 0, v[134:135]
	s_mov_b32 m0, s15
	s_nop 0
	global_load_lds_dwordx4 v[224:225], off
	s_mov_b32 m0, s46
	s_nop 0
	global_load_lds_dwordx4 v[226:227], off
	s_waitcnt vmcnt(8)
	s_waitcnt lgkmcnt(0)
	s_barrier
	s_setprio 1
	v_mfma_f32_16x16x32_bf16 v[60:63], v[156:159], v[188:191], v[60:63]
	v_mfma_f32_16x16x32_bf16 v[56:59], v[164:167], v[188:191], v[56:59]
	v_mfma_f32_16x16x32_bf16 v[44:47], v[156:159], v[198:201], v[44:47]
	v_mfma_f32_16x16x32_bf16 v[40:43], v[164:167], v[198:201], v[40:43]
	v_mfma_f32_16x16x32_bf16 v[28:31], v[156:159], v[206:209], v[28:31]
	v_mfma_f32_16x16x32_bf16 v[24:27], v[164:167], v[206:209], v[24:27]
	v_mfma_f32_16x16x32_bf16 v[12:15], v[156:159], v[214:217], v[12:15]
	v_mfma_f32_16x16x32_bf16 v[8:11], v[164:167], v[214:217], v[8:11]
	v_mfma_f32_16x16x32_bf16 v[60:63], v[160:163], v[192:195], v[60:63]
	v_mfma_f32_16x16x32_bf16 v[56:59], v[168:171], v[192:195], v[56:59]
	v_mfma_f32_16x16x32_bf16 v[44:47], v[160:163], v[202:205], v[44:47]
	v_mfma_f32_16x16x32_bf16 v[40:43], v[168:171], v[202:205], v[40:43]
	v_mfma_f32_16x16x32_bf16 v[28:31], v[160:163], v[210:213], v[28:31]
	v_mfma_f32_16x16x32_bf16 v[24:27], v[168:171], v[210:213], v[24:27]
	v_mfma_f32_16x16x32_bf16 v[12:15], v[160:163], v[218:221], v[12:15]
	v_mfma_f32_16x16x32_bf16 v[8:11], v[168:171], v[218:221], v[8:11]
	v_mfma_f32_16x16x32_bf16 v[52:55], v[172:175], v[188:191], v[52:55]
	v_mfma_f32_16x16x32_bf16 v[48:51], v[180:183], v[188:191], v[48:51]
	v_mfma_f32_16x16x32_bf16 v[36:39], v[172:175], v[198:201], v[36:39]
	v_mfma_f32_16x16x32_bf16 v[32:35], v[180:183], v[198:201], v[32:35]
	v_mfma_f32_16x16x32_bf16 v[20:23], v[172:175], v[206:209], v[20:23]
	v_mfma_f32_16x16x32_bf16 v[16:19], v[180:183], v[206:209], v[16:19]
	v_mfma_f32_16x16x32_bf16 v[4:7], v[172:175], v[214:217], v[4:7]
	v_mfma_f32_16x16x32_bf16 v[0:3], v[180:183], v[214:217], v[0:3]
	v_mfma_f32_16x16x32_bf16 v[52:55], v[176:179], v[192:195], v[52:55]
	v_mfma_f32_16x16x32_bf16 v[48:51], v[184:187], v[192:195], v[48:51]
	v_mfma_f32_16x16x32_bf16 v[36:39], v[176:179], v[202:205], v[36:39]
	v_mfma_f32_16x16x32_bf16 v[32:35], v[184:187], v[202:205], v[32:35]
	v_mfma_f32_16x16x32_bf16 v[20:23], v[176:179], v[210:213], v[20:23]
	v_mfma_f32_16x16x32_bf16 v[16:19], v[184:187], v[210:213], v[16:19]
	v_mfma_f32_16x16x32_bf16 v[4:7], v[176:179], v[218:221], v[4:7]
	v_mfma_f32_16x16x32_bf16 v[0:3], v[184:187], v[218:221], v[0:3]
	s_setprio 0
	s_barrier
	s_add_i32 s64, 0, 0x18000
	v_add_u32_e32 v136, s64, v150
	s_add_i32 s65, 0, 0x1c000
	ds_read_b128 v[156:159], v136
	ds_read_b128 v[160:163], v136 offset:1024
	ds_read_b128 v[164:167], v136 offset:2048
	ds_read_b128 v[168:171], v136 offset:3072
	v_add_u32_e32 v136, s65, v150
	ds_read_b128 v[172:175], v136
	ds_read_b128 v[176:179], v136 offset:1024
	ds_read_b128 v[180:183], v136 offset:2048
	ds_read_b128 v[184:187], v136 offset:3072
	s_add_u32 s44, s44, 0x40000
	s_addc_u32 s45, s45, 0
	s_mov_b32 m0, s47
	v_lshl_add_u64 v[228:229], s[44:45], 0, v[134:135]
	ds_read_b128 v[188:191], v153 offset:32768
	ds_read_b128 v[192:195], v153 offset:33792
	ds_read_b128 v[198:201], v153 offset:34816
	ds_read_b128 v[202:205], v153 offset:35840
	ds_read_b128 v[206:209], v153 offset:36864
	ds_read_b128 v[210:213], v153 offset:37888
	ds_read_b128 v[214:217], v153 offset:38912
	ds_read_b128 v[218:221], v153 offset:39936
	global_load_lds_dwordx4 v[228:229], off
	v_lshl_add_u64 v[228:229], s[44:45], 0, v[130:131]
	s_mov_b32 m0, s48
	s_nop 0
	global_load_lds_dwordx4 v[228:229], off
	s_waitcnt vmcnt(8)
	s_waitcnt lgkmcnt(0)
	s_barrier
	s_setprio 1
	v_mfma_f32_16x16x32_bf16 v[124:127], v[156:159], v[188:191], v[124:127]
	v_mfma_f32_16x16x32_bf16 v[120:123], v[164:167], v[188:191], v[120:123]
	v_mfma_f32_16x16x32_bf16 v[108:111], v[156:159], v[198:201], v[108:111]
	v_mfma_f32_16x16x32_bf16 v[104:107], v[164:167], v[198:201], v[104:107]
	v_mfma_f32_16x16x32_bf16 v[92:95], v[156:159], v[206:209], v[92:95]
	v_mfma_f32_16x16x32_bf16 v[88:91], v[164:167], v[206:209], v[88:91]
	v_mfma_f32_16x16x32_bf16 v[76:79], v[156:159], v[214:217], v[76:79]
	v_mfma_f32_16x16x32_bf16 v[72:75], v[164:167], v[214:217], v[72:75]
	v_mfma_f32_16x16x32_bf16 v[124:127], v[160:163], v[192:195], v[124:127]
	v_mfma_f32_16x16x32_bf16 v[120:123], v[168:171], v[192:195], v[120:123]
	v_mfma_f32_16x16x32_bf16 v[108:111], v[160:163], v[202:205], v[108:111]
	v_mfma_f32_16x16x32_bf16 v[104:107], v[168:171], v[202:205], v[104:107]
	v_mfma_f32_16x16x32_bf16 v[92:95], v[160:163], v[210:213], v[92:95]
	v_mfma_f32_16x16x32_bf16 v[88:91], v[168:171], v[210:213], v[88:91]
	v_mfma_f32_16x16x32_bf16 v[76:79], v[160:163], v[218:221], v[76:79]
	v_mfma_f32_16x16x32_bf16 v[72:75], v[168:171], v[218:221], v[72:75]
	v_mfma_f32_16x16x32_bf16 v[116:119], v[172:175], v[188:191], v[116:119]
	v_mfma_f32_16x16x32_bf16 v[112:115], v[180:183], v[188:191], v[112:115]
	v_mfma_f32_16x16x32_bf16 v[100:103], v[172:175], v[198:201], v[100:103]
	v_mfma_f32_16x16x32_bf16 v[96:99], v[180:183], v[198:201], v[96:99]
	v_mfma_f32_16x16x32_bf16 v[84:87], v[172:175], v[206:209], v[84:87]
	v_mfma_f32_16x16x32_bf16 v[80:83], v[180:183], v[206:209], v[80:83]
	v_mfma_f32_16x16x32_bf16 v[68:71], v[172:175], v[214:217], v[68:71]
	v_mfma_f32_16x16x32_bf16 v[64:67], v[180:183], v[214:217], v[64:67]
	v_mfma_f32_16x16x32_bf16 v[116:119], v[176:179], v[192:195], v[116:119]
	v_mfma_f32_16x16x32_bf16 v[112:115], v[184:187], v[192:195], v[112:115]
	v_mfma_f32_16x16x32_bf16 v[100:103], v[176:179], v[202:205], v[100:103]
	v_mfma_f32_16x16x32_bf16 v[96:99], v[184:187], v[202:205], v[96:99]
	v_mfma_f32_16x16x32_bf16 v[84:87], v[176:179], v[210:213], v[84:87]
	v_mfma_f32_16x16x32_bf16 v[80:83], v[184:187], v[210:213], v[80:83]
	v_mfma_f32_16x16x32_bf16 v[68:71], v[176:179], v[218:221], v[68:71]
	v_mfma_f32_16x16x32_bf16 v[64:67], v[184:187], v[218:221], v[64:67]
	s_setprio 0
	s_barrier
	s_add_i32 s44, s64, s2
	v_lshl_add_u64 v[148:149], v[148:149], 0, s[16:17]
	s_mov_b32 m0, s44
	ds_read_b128 v[188:191], v153 offset:49152
	ds_read_b128 v[192:195], v153 offset:50176
	ds_read_b128 v[198:201], v153 offset:51200
	ds_read_b128 v[202:205], v153 offset:52224
	ds_read_b128 v[206:209], v153 offset:53248
	ds_read_b128 v[210:213], v153 offset:54272
	ds_read_b128 v[214:217], v153 offset:55296
	ds_read_b128 v[218:221], v153 offset:56320
	global_load_lds_dwordx4 v[148:149], off
	s_add_i32 m0, s44, 0x2000
	s_add_u32 s40, s40, 0x40080
	v_lshl_add_u64 v[148:149], v[222:223], 0, s[16:17]
	s_addc_u32 s41, s41, 0
	s_add_i32 s44, s65, s2
	global_load_lds_dwordx4 v[148:149], off
	v_lshl_add_u64 v[148:149], s[40:41], 0, v[132:133]
	s_mov_b32 m0, s44
	s_nop 0
	global_load_lds_dwordx4 v[148:149], off
	v_lshl_add_u64 v[148:149], s[40:41], 0, v[128:129]
	s_add_i32 m0, s44, 0x2000
	s_nop 0
	global_load_lds_dwordx4 v[148:149], off
	v_lshl_add_u64 v[148:149], v[224:225], 0, s[16:17]
	s_mov_b32 m0, s54
	s_nop 0
	global_load_lds_dwordx4 v[148:149], off
	v_lshl_add_u64 v[148:149], v[226:227], 0, s[16:17]
	s_mov_b32 m0, s55
	s_nop 0
	global_load_lds_dwordx4 v[148:149], off
	s_waitcnt vmcnt(8)
	s_waitcnt lgkmcnt(0)
	s_barrier
	s_setprio 1
	v_mfma_f32_16x16x32_bf16 v[60:63], v[156:159], v[188:191], v[60:63]
	v_mfma_f32_16x16x32_bf16 v[56:59], v[164:167], v[188:191], v[56:59]
	v_mfma_f32_16x16x32_bf16 v[44:47], v[156:159], v[198:201], v[44:47]
	v_mfma_f32_16x16x32_bf16 v[40:43], v[164:167], v[198:201], v[40:43]
	v_mfma_f32_16x16x32_bf16 v[28:31], v[156:159], v[206:209], v[28:31]
	v_mfma_f32_16x16x32_bf16 v[24:27], v[164:167], v[206:209], v[24:27]
	v_mfma_f32_16x16x32_bf16 v[12:15], v[156:159], v[214:217], v[12:15]
	v_mfma_f32_16x16x32_bf16 v[8:11], v[164:167], v[214:217], v[8:11]
	v_mfma_f32_16x16x32_bf16 v[60:63], v[160:163], v[192:195], v[60:63]
	v_mfma_f32_16x16x32_bf16 v[56:59], v[168:171], v[192:195], v[56:59]
	v_mfma_f32_16x16x32_bf16 v[44:47], v[160:163], v[202:205], v[44:47]
	v_mfma_f32_16x16x32_bf16 v[40:43], v[168:171], v[202:205], v[40:43]
	v_mfma_f32_16x16x32_bf16 v[28:31], v[160:163], v[210:213], v[28:31]
	v_mfma_f32_16x16x32_bf16 v[24:27], v[168:171], v[210:213], v[24:27]
	v_mfma_f32_16x16x32_bf16 v[12:15], v[160:163], v[218:221], v[12:15]
	v_mfma_f32_16x16x32_bf16 v[8:11], v[168:171], v[218:221], v[8:11]
	v_mfma_f32_16x16x32_bf16 v[52:55], v[172:175], v[188:191], v[52:55]
	v_mfma_f32_16x16x32_bf16 v[48:51], v[180:183], v[188:191], v[48:51]
	v_mfma_f32_16x16x32_bf16 v[36:39], v[172:175], v[198:201], v[36:39]
	v_mfma_f32_16x16x32_bf16 v[32:35], v[180:183], v[198:201], v[32:35]
	v_mfma_f32_16x16x32_bf16 v[20:23], v[172:175], v[206:209], v[20:23]
	v_mfma_f32_16x16x32_bf16 v[16:19], v[180:183], v[206:209], v[16:19]
	v_mfma_f32_16x16x32_bf16 v[4:7], v[172:175], v[214:217], v[4:7]
	v_mfma_f32_16x16x32_bf16 v[0:3], v[180:183], v[214:217], v[0:3]
	v_mfma_f32_16x16x32_bf16 v[52:55], v[176:179], v[192:195], v[52:55]
	v_mfma_f32_16x16x32_bf16 v[48:51], v[184:187], v[192:195], v[48:51]
	v_mfma_f32_16x16x32_bf16 v[36:39], v[176:179], v[202:205], v[36:39]
	v_mfma_f32_16x16x32_bf16 v[32:35], v[184:187], v[202:205], v[32:35]
	v_mfma_f32_16x16x32_bf16 v[20:23], v[176:179], v[210:213], v[20:23]
	v_mfma_f32_16x16x32_bf16 v[16:19], v[184:187], v[210:213], v[16:19]
	v_mfma_f32_16x16x32_bf16 v[4:7], v[176:179], v[218:221], v[4:7]
	v_mfma_f32_16x16x32_bf16 v[0:3], v[184:187], v[218:221], v[0:3]
	s_setprio 0
	s_barrier
	s_add_i32 s63, s63, 2
	s_add_u32 s36, s36, 0x100
	s_addc_u32 s37, s37, 0
	s_add_u32 s61, s61, 0x100
	s_addc_u32 s62, s62, 0
	s_cmp_gt_u32 s63, 13
	s_cbranch_scc0 .LBB0_1122
	s_and_b64 vcc, exec, s[18:19]
	s_cbranch_vccz .LBB0_1125
	s_barrier

.LBB0_1203:
	ds_read_b128 v[144:147], v153
	ds_read_b128 v[156:159], v153 offset:1024
	ds_read_b128 v[160:163], v153 offset:2048
	ds_read_b128 v[164:167], v153 offset:3072
	ds_read_b128 v[168:171], v154
	ds_read_b128 v[172:175], v154 offset:1024
	ds_read_b128 v[176:179], v154 offset:2048
	ds_read_b128 v[180:183], v154 offset:3072
	s_add_u32 s18, s16, 0x100
	s_addc_u32 s19, s17, 0
	s_cmp_eq_u32 s50, 40
	s_cselect_b32 s23, s5, s19
	s_cselect_b32 s22, s4, s18
	s_cselect_b32 s21, s15, s49
	s_cselect_b32 s20, s14, s48
	v_lshl_add_u64 v[148:149], s[16:17], 0, v[136:137]
	s_add_i32 m0, s24, 0xc000
	ds_read_b128 v[184:187], v155
	ds_read_b128 v[188:191], v155 offset:1024
	ds_read_b128 v[192:195], v155 offset:2048
	ds_read_b128 v[196:199], v155 offset:3072
	ds_read_b128 v[200:203], v155 offset:4096
	ds_read_b128 v[204:207], v155 offset:5120
	ds_read_b128 v[208:211], v155 offset:6144
	ds_read_b128 v[212:215], v155 offset:7168
	global_load_lds_dwordx4 v[148:149], off
	v_lshl_add_u64 v[148:149], s[16:17], 0, v[138:139]
	s_add_i32 m0, s24, 0xe000
	s_nop 0
	global_load_lds_dwordx4 v[148:149], off
	s_waitcnt vmcnt(8)
	s_waitcnt lgkmcnt(0)
	s_barrier
	s_setprio 1
	v_mfma_f32_16x16x32_bf16 v[124:127], v[144:147], v[184:187], v[124:127]
	v_mfma_f32_16x16x32_bf16 v[120:123], v[160:163], v[184:187], v[120:123]
	v_mfma_f32_16x16x32_bf16 v[108:111], v[144:147], v[192:195], v[108:111]
	v_mfma_f32_16x16x32_bf16 v[104:107], v[160:163], v[192:195], v[104:107]
	v_mfma_f32_16x16x32_bf16 v[92:95], v[144:147], v[200:203], v[92:95]
	v_mfma_f32_16x16x32_bf16 v[88:91], v[160:163], v[200:203], v[88:91]
	v_mfma_f32_16x16x32_bf16 v[76:79], v[144:147], v[208:211], v[76:79]
	v_mfma_f32_16x16x32_bf16 v[72:75], v[160:163], v[208:211], v[72:75]
	v_mfma_f32_16x16x32_bf16 v[124:127], v[156:159], v[188:191], v[124:127]
	v_mfma_f32_16x16x32_bf16 v[120:123], v[164:167], v[188:191], v[120:123]
	v_mfma_f32_16x16x32_bf16 v[108:111], v[156:159], v[196:199], v[108:111]
	v_mfma_f32_16x16x32_bf16 v[104:107], v[164:167], v[196:199], v[104:107]
	v_mfma_f32_16x16x32_bf16 v[92:95], v[156:159], v[204:207], v[92:95]
	v_mfma_f32_16x16x32_bf16 v[88:91], v[164:167], v[204:207], v[88:91]
	v_mfma_f32_16x16x32_bf16 v[76:79], v[156:159], v[212:215], v[76:79]
	v_mfma_f32_16x16x32_bf16 v[72:75], v[164:167], v[212:215], v[72:75]
	v_mfma_f32_16x16x32_bf16 v[116:119], v[168:171], v[184:187], v[116:119]
	v_mfma_f32_16x16x32_bf16 v[112:115], v[176:179], v[184:187], v[112:115]
	v_mfma_f32_16x16x32_bf16 v[100:103], v[168:171], v[192:195], v[100:103]
	v_mfma_f32_16x16x32_bf16 v[96:99], v[176:179], v[192:195], v[96:99]
	v_mfma_f32_16x16x32_bf16 v[84:87], v[168:171], v[200:203], v[84:87]
	v_mfma_f32_16x16x32_bf16 v[80:83], v[176:179], v[200:203], v[80:83]
	v_mfma_f32_16x16x32_bf16 v[68:71], v[168:171], v[208:211], v[68:71]
	v_mfma_f32_16x16x32_bf16 v[64:67], v[176:179], v[208:211], v[64:67]
	v_mfma_f32_16x16x32_bf16 v[116:119], v[172:175], v[188:191], v[116:119]
	v_mfma_f32_16x16x32_bf16 v[112:115], v[180:183], v[188:191], v[112:115]
	v_mfma_f32_16x16x32_bf16 v[100:103], v[172:175], v[196:199], v[100:103]
	v_mfma_f32_16x16x32_bf16 v[96:99], v[180:183], v[196:199], v[96:99]
	v_mfma_f32_16x16x32_bf16 v[84:87], v[172:175], v[204:207], v[84:87]
	v_mfma_f32_16x16x32_bf16 v[80:83], v[180:183], v[204:207], v[80:83]
	v_mfma_f32_16x16x32_bf16 v[68:71], v[172:175], v[212:215], v[68:71]
	v_mfma_f32_16x16x32_bf16 v[64:67], v[180:183], v[212:215], v[64:67]
	s_setprio 0
	s_barrier
	s_add_i32 s16, s42, s3
	v_lshl_add_u64 v[148:149], s[20:21], 0, v[130:131]
	s_mov_b32 m0, s16
	ds_read_b128 v[184:187], v155 offset:16384
	ds_read_b128 v[188:191], v155 offset:17408
	ds_read_b128 v[192:195], v155 offset:18432
	ds_read_b128 v[196:199], v155 offset:19456
	ds_read_b128 v[200:203], v155 offset:20480
	ds_read_b128 v[204:207], v155 offset:21504
	ds_read_b128 v[208:211], v155 offset:22528
	ds_read_b128 v[212:215], v155 offset:23552
	global_load_lds_dwordx4 v[148:149], off
	s_add_i32 m0, s16, 0x2000
	s_add_u32 s16, s20, 0xb0000
	v_lshl_add_u64 v[216:217], s[20:21], 0, v[134:135]
	s_addc_u32 s17, s21, 0
	s_add_i32 s51, s43, s3
	global_load_lds_dwordx4 v[216:217], off
	v_lshl_add_u64 v[218:219], s[16:17], 0, v[130:131]
	s_mov_b32 m0, s51
	v_lshl_add_u64 v[220:221], s[22:23], 0, v[132:133]
	global_load_lds_dwordx4 v[218:219], off
	v_lshl_add_u64 v[218:219], s[16:17], 0, v[134:135]
	s_add_i32 m0, s51, 0x2000
	s_nop 0
	global_load_lds_dwordx4 v[218:219], off
	v_lshl_add_u64 v[218:219], s[22:23], 0, v[128:129]
	s_mov_b32 m0, s24
	s_nop 0
	global_load_lds_dwordx4 v[218:219], off
	s_mov_b32 m0, s25
	s_nop 0
	global_load_lds_dwordx4 v[220:221], off
	s_waitcnt vmcnt(8)
	s_waitcnt lgkmcnt(0)
	s_barrier
	s_setprio 1
	v_mfma_f32_16x16x32_bf16 v[60:63], v[144:147], v[184:187], v[60:63]
	v_mfma_f32_16x16x32_bf16 v[56:59], v[160:163], v[184:187], v[56:59]
	v_mfma_f32_16x16x32_bf16 v[44:47], v[144:147], v[192:195], v[44:47]
	v_mfma_f32_16x16x32_bf16 v[40:43], v[160:163], v[192:195], v[40:43]
	v_mfma_f32_16x16x32_bf16 v[28:31], v[144:147], v[200:203], v[28:31]
	v_mfma_f32_16x16x32_bf16 v[24:27], v[160:163], v[200:203], v[24:27]
	v_mfma_f32_16x16x32_bf16 v[12:15], v[144:147], v[208:211], v[12:15]
	v_mfma_f32_16x16x32_bf16 v[8:11], v[160:163], v[208:211], v[8:11]
	v_mfma_f32_16x16x32_bf16 v[60:63], v[156:159], v[188:191], v[60:63]
	v_mfma_f32_16x16x32_bf16 v[56:59], v[164:167], v[188:191], v[56:59]
	v_mfma_f32_16x16x32_bf16 v[44:47], v[156:159], v[196:199], v[44:47]
	v_mfma_f32_16x16x32_bf16 v[40:43], v[164:167], v[196:199], v[40:43]
	v_mfma_f32_16x16x32_bf16 v[28:31], v[156:159], v[204:207], v[28:31]
	v_mfma_f32_16x16x32_bf16 v[24:27], v[164:167], v[204:207], v[24:27]
	v_mfma_f32_16x16x32_bf16 v[12:15], v[156:159], v[212:215], v[12:15]
	v_mfma_f32_16x16x32_bf16 v[8:11], v[164:167], v[212:215], v[8:11]
	v_mfma_f32_16x16x32_bf16 v[52:55], v[168:171], v[184:187], v[52:55]
	v_mfma_f32_16x16x32_bf16 v[48:51], v[176:179], v[184:187], v[48:51]
	v_mfma_f32_16x16x32_bf16 v[36:39], v[168:171], v[192:195], v[36:39]
	v_mfma_f32_16x16x32_bf16 v[32:35], v[176:179], v[192:195], v[32:35]
	v_mfma_f32_16x16x32_bf16 v[20:23], v[168:171], v[200:203], v[20:23]
	v_mfma_f32_16x16x32_bf16 v[16:19], v[176:179], v[200:203], v[16:19]
	v_mfma_f32_16x16x32_bf16 v[4:7], v[168:171], v[208:211], v[4:7]
	v_mfma_f32_16x16x32_bf16 v[0:3], v[176:179], v[208:211], v[0:3]
	v_mfma_f32_16x16x32_bf16 v[52:55], v[172:175], v[188:191], v[52:55]
	v_mfma_f32_16x16x32_bf16 v[48:51], v[180:183], v[188:191], v[48:51]
	v_mfma_f32_16x16x32_bf16 v[36:39], v[172:175], v[196:199], v[36:39]
	v_mfma_f32_16x16x32_bf16 v[32:35], v[180:183], v[196:199], v[32:35]
	v_mfma_f32_16x16x32_bf16 v[20:23], v[172:175], v[204:207], v[20:23]
	v_mfma_f32_16x16x32_bf16 v[16:19], v[180:183], v[204:207], v[16:19]
	v_mfma_f32_16x16x32_bf16 v[4:7], v[172:175], v[212:215], v[4:7]
	v_mfma_f32_16x16x32_bf16 v[0:3], v[180:183], v[212:215], v[0:3]
	s_setprio 0
	s_barrier
	s_add_i32 s51, 0, 0x18000
	s_add_i32 s52, 0, 0x1c000
	v_add_u32_e32 v164, s51, v151
	v_add_u32_e32 v180, s52, v151
	ds_read_b128 v[144:147], v164
	ds_read_b128 v[156:159], v164 offset:1024
	ds_read_b128 v[160:163], v164 offset:2048
	ds_read_b128 v[164:167], v164 offset:3072
	ds_read_b128 v[168:171], v180
	ds_read_b128 v[172:175], v180 offset:1024
	ds_read_b128 v[176:179], v180 offset:2048
	ds_read_b128 v[180:183], v180 offset:3072
	s_add_u32 s16, s22, 0xb0000
	s_addc_u32 s17, s23, 0
	s_mov_b32 m0, s26
	v_lshl_add_u64 v[222:223], s[16:17], 0, v[128:129]
	ds_read_b128 v[184:187], v155 offset:32768
	ds_read_b128 v[188:191], v155 offset:33792
	ds_read_b128 v[192:195], v155 offset:34816
	ds_read_b128 v[196:199], v155 offset:35840
	ds_read_b128 v[200:203], v155 offset:36864
	ds_read_b128 v[204:207], v155 offset:37888
	ds_read_b128 v[208:211], v155 offset:38912
	ds_read_b128 v[212:215], v155 offset:39936
	global_load_lds_dwordx4 v[222:223], off
	v_lshl_add_u64 v[222:223], s[16:17], 0, v[132:133]
	s_mov_b32 m0, s27
	s_nop 0
	global_load_lds_dwordx4 v[222:223], off
	s_waitcnt vmcnt(8)
	s_waitcnt lgkmcnt(0)
	s_barrier
	s_setprio 1
	v_mfma_f32_16x16x32_bf16 v[124:127], v[144:147], v[184:187], v[124:127]
	v_mfma_f32_16x16x32_bf16 v[120:123], v[160:163], v[184:187], v[120:123]
	v_mfma_f32_16x16x32_bf16 v[108:111], v[144:147], v[192:195], v[108:111]
	v_mfma_f32_16x16x32_bf16 v[104:107], v[160:163], v[192:195], v[104:107]
	v_mfma_f32_16x16x32_bf16 v[92:95], v[144:147], v[200:203], v[92:95]
	v_mfma_f32_16x16x32_bf16 v[88:91], v[160:163], v[200:203], v[88:91]
	v_mfma_f32_16x16x32_bf16 v[76:79], v[144:147], v[208:211], v[76:79]
	v_mfma_f32_16x16x32_bf16 v[72:75], v[160:163], v[208:211], v[72:75]
	v_mfma_f32_16x16x32_bf16 v[124:127], v[156:159], v[188:191], v[124:127]
	v_mfma_f32_16x16x32_bf16 v[120:123], v[164:167], v[188:191], v[120:123]
	v_mfma_f32_16x16x32_bf16 v[108:111], v[156:159], v[196:199], v[108:111]
	v_mfma_f32_16x16x32_bf16 v[104:107], v[164:167], v[196:199], v[104:107]
	v_mfma_f32_16x16x32_bf16 v[92:95], v[156:159], v[204:207], v[92:95]
	v_mfma_f32_16x16x32_bf16 v[88:91], v[164:167], v[204:207], v[88:91]
	v_mfma_f32_16x16x32_bf16 v[76:79], v[156:159], v[212:215], v[76:79]
	v_mfma_f32_16x16x32_bf16 v[72:75], v[164:167], v[212:215], v[72:75]
	v_mfma_f32_16x16x32_bf16 v[116:119], v[168:171], v[184:187], v[116:119]
	v_mfma_f32_16x16x32_bf16 v[112:115], v[176:179], v[184:187], v[112:115]
	v_mfma_f32_16x16x32_bf16 v[100:103], v[168:171], v[192:195], v[100:103]
	v_mfma_f32_16x16x32_bf16 v[96:99], v[176:179], v[192:195], v[96:99]
	v_mfma_f32_16x16x32_bf16 v[84:87], v[168:171], v[200:203], v[84:87]
	v_mfma_f32_16x16x32_bf16 v[80:83], v[176:179], v[200:203], v[80:83]
	v_mfma_f32_16x16x32_bf16 v[68:71], v[168:171], v[208:211], v[68:71]
	v_mfma_f32_16x16x32_bf16 v[64:67], v[176:179], v[208:211], v[64:67]
	v_mfma_f32_16x16x32_bf16 v[116:119], v[172:175], v[188:191], v[116:119]
	v_mfma_f32_16x16x32_bf16 v[112:115], v[180:183], v[188:191], v[112:115]
	v_mfma_f32_16x16x32_bf16 v[100:103], v[172:175], v[196:199], v[100:103]
	v_mfma_f32_16x16x32_bf16 v[96:99], v[180:183], v[196:199], v[96:99]
	v_mfma_f32_16x16x32_bf16 v[84:87], v[172:175], v[204:207], v[84:87]
	v_mfma_f32_16x16x32_bf16 v[80:83], v[180:183], v[204:207], v[80:83]
	v_mfma_f32_16x16x32_bf16 v[68:71], v[172:175], v[212:215], v[68:71]
	v_mfma_f32_16x16x32_bf16 v[64:67], v[180:183], v[212:215], v[64:67]
	s_setprio 0
	s_barrier
	s_add_i32 s16, s51, s3
	v_lshl_add_u64 v[148:149], v[148:149], 0, s[10:11]
	s_mov_b32 m0, s16
	ds_read_b128 v[184:187], v155 offset:49152
	ds_read_b128 v[188:191], v155 offset:50176
	ds_read_b128 v[192:195], v155 offset:51200
	ds_read_b128 v[196:199], v155 offset:52224
	ds_read_b128 v[200:203], v155 offset:53248
	ds_read_b128 v[204:207], v155 offset:54272
	ds_read_b128 v[208:211], v155 offset:55296
	ds_read_b128 v[212:215], v155 offset:56320
	global_load_lds_dwordx4 v[148:149], off
	s_add_i32 m0, s16, 0x2000
	s_add_u32 s16, s20, 0xb0080
	v_lshl_add_u64 v[148:149], v[216:217], 0, s[10:11]
	s_addc_u32 s17, s21, 0
	s_add_i32 s20, s52, s3
	global_load_lds_dwordx4 v[148:149], off
	v_lshl_add_u64 v[148:149], s[16:17], 0, v[130:131]
	s_mov_b32 m0, s20
	s_nop 0
	global_load_lds_dwordx4 v[148:149], off
	v_lshl_add_u64 v[148:149], s[16:17], 0, v[134:135]
	s_add_i32 m0, s20, 0x2000
	s_nop 0
	global_load_lds_dwordx4 v[148:149], off
	v_lshl_add_u64 v[148:149], v[218:219], 0, s[10:11]
	s_mov_b32 m0, s37
	s_nop 0
	global_load_lds_dwordx4 v[148:149], off
	v_lshl_add_u64 v[148:149], v[220:221], 0, s[10:11]
	s_mov_b32 m0, s40
	s_nop 0
	global_load_lds_dwordx4 v[148:149], off
	s_waitcnt vmcnt(8)
	s_waitcnt lgkmcnt(0)
	s_barrier
	s_setprio 1
	v_mfma_f32_16x16x32_bf16 v[60:63], v[144:147], v[184:187], v[60:63]
	v_mfma_f32_16x16x32_bf16 v[56:59], v[160:163], v[184:187], v[56:59]
	v_mfma_f32_16x16x32_bf16 v[44:47], v[144:147], v[192:195], v[44:47]
	v_mfma_f32_16x16x32_bf16 v[40:43], v[160:163], v[192:195], v[40:43]
	v_mfma_f32_16x16x32_bf16 v[28:31], v[144:147], v[200:203], v[28:31]
	v_mfma_f32_16x16x32_bf16 v[24:27], v[160:163], v[200:203], v[24:27]
	v_mfma_f32_16x16x32_bf16 v[12:15], v[144:147], v[208:211], v[12:15]
	v_mfma_f32_16x16x32_bf16 v[8:11], v[160:163], v[208:211], v[8:11]
	v_mfma_f32_16x16x32_bf16 v[60:63], v[156:159], v[188:191], v[60:63]
	v_mfma_f32_16x16x32_bf16 v[56:59], v[164:167], v[188:191], v[56:59]
	v_mfma_f32_16x16x32_bf16 v[44:47], v[156:159], v[196:199], v[44:47]
	v_mfma_f32_16x16x32_bf16 v[40:43], v[164:167], v[196:199], v[40:43]
	v_mfma_f32_16x16x32_bf16 v[28:31], v[156:159], v[204:207], v[28:31]
	v_mfma_f32_16x16x32_bf16 v[24:27], v[164:167], v[204:207], v[24:27]
	v_mfma_f32_16x16x32_bf16 v[12:15], v[156:159], v[212:215], v[12:15]
	v_mfma_f32_16x16x32_bf16 v[8:11], v[164:167], v[212:215], v[8:11]
	v_mfma_f32_16x16x32_bf16 v[52:55], v[168:171], v[184:187], v[52:55]
	v_mfma_f32_16x16x32_bf16 v[48:51], v[176:179], v[184:187], v[48:51]
	v_mfma_f32_16x16x32_bf16 v[36:39], v[168:171], v[192:195], v[36:39]
	v_mfma_f32_16x16x32_bf16 v[32:35], v[176:179], v[192:195], v[32:35]
	v_mfma_f32_16x16x32_bf16 v[20:23], v[168:171], v[200:203], v[20:23]
	v_mfma_f32_16x16x32_bf16 v[16:19], v[176:179], v[200:203], v[16:19]
	v_mfma_f32_16x16x32_bf16 v[4:7], v[168:171], v[208:211], v[4:7]
	v_mfma_f32_16x16x32_bf16 v[0:3], v[176:179], v[208:211], v[0:3]
	v_mfma_f32_16x16x32_bf16 v[52:55], v[172:175], v[188:191], v[52:55]
	v_mfma_f32_16x16x32_bf16 v[48:51], v[180:183], v[188:191], v[48:51]
	v_mfma_f32_16x16x32_bf16 v[36:39], v[172:175], v[196:199], v[36:39]
	v_mfma_f32_16x16x32_bf16 v[32:35], v[180:183], v[196:199], v[32:35]
	v_mfma_f32_16x16x32_bf16 v[20:23], v[172:175], v[204:207], v[20:23]
	v_mfma_f32_16x16x32_bf16 v[16:19], v[180:183], v[204:207], v[16:19]
	v_mfma_f32_16x16x32_bf16 v[4:7], v[172:175], v[212:215], v[4:7]
	v_mfma_f32_16x16x32_bf16 v[0:3], v[180:183], v[212:215], v[0:3]
	s_setprio 0
	s_barrier
	s_add_i32 s50, s50, 2
	s_add_u32 s48, s48, 0x100
	s_addc_u32 s49, s49, 0
	s_cmp_gt_u32 s50, 41
	s_mov_b64 s[16:17], s[18:19]
	s_cbranch_scc0 .LBB0_1203
	s_and_b64 vcc, exec, s[12:13]
	s_cbranch_vccz .LBB0_1206
	s_barrier
